# diff attention fast loops: softmax row-sum chain rewritten from compiler-packed v_pk_add_f32 + copies + pads to the same additions with plain v_add_f32 (bit-identical)
# speedup vs baseline: 1.0004x; 1.0004x over previous
.LBB0_797:
	ds_read_b128 v[188:191], v207 offset:45056
	ds_read_b128 v[112:115], v207 offset:40960
	v_exp_f32_e32 v152, v80
	v_exp_f32_e32 v167, v81
	v_exp_f32_e32 v169, v82
	v_exp_f32_e32 v171, v83
	s_waitcnt lgkmcnt(0)
	v_mfma_f32_32x32x16_bf16 v[96:111], v[112:115], v[140:143], v[64:79]
	v_exp_f32_e32 v173, v84
	v_add_f32_e32 v80, v183, v152
	v_add_f32_e32 v80, 0, v80
	v_add_f32_e32 v81, v168, v167
	v_add_f32_e32 v80, v81, v80
	v_add_f32_e32 v81, v185, v169
	v_add_f32_e32 v80, v81, v80
	v_mfma_f32_32x32x16_bf16 v[112:127], v[188:191], v[140:143], v[64:79]
	ds_read_b128 v[188:191], v208 offset:45056
	ds_read_b128 v[192:195], v208 offset:40960
	v_add_f32_e32 v81, v166, v171
	v_exp_f32_e32 v154, v88
	v_exp_f32_e32 v155, v89
	v_add_f32_e32 v80, v81, v80
	v_add_f32_e32 v81, v186, v173
	v_add_f32_e32 v80, v81, v80
	s_waitcnt lgkmcnt(1)
	v_mfma_f32_32x32x16_bf16 v[112:127], v[188:191], v[136:139], v[112:127]
	v_exp_f32_e32 v156, v90
	v_exp_f32_e32 v157, v91
	v_exp_f32_e32 v158, v92
	v_exp_f32_e32 v159, v93
	v_exp_f32_e32 v160, v94
	v_exp_f32_e32 v161, v95
	s_waitcnt lgkmcnt(0)
	v_mfma_f32_32x32x16_bf16 v[96:111], v[192:195], v[136:139], v[96:111]
	ds_read_b128 v[188:191], v213 offset:45056
	ds_read_b128 v[192:195], v213 offset:40960
	s_waitcnt lgkmcnt(1)
	v_mfma_f32_32x32x16_bf16 v[112:127], v[188:191], v[132:135], v[112:127]
	s_waitcnt lgkmcnt(0)
	v_mfma_f32_32x32x16_bf16 v[96:111], v[192:195], v[132:135], v[96:111]
	ds_read_b128 v[188:191], v212 offset:45056
	ds_read_b128 v[192:195], v212 offset:40960
	s_waitcnt lgkmcnt(1)
	v_mfma_f32_32x32x16_bf16 v[112:127], v[188:191], v[128:131], v[112:127]
	v_exp_f32_e32 v188, v85
	v_exp_f32_e32 v189, v86
	v_exp_f32_e32 v190, v87
	v_add_f32_e32 v81, v172, v188
	v_add_f32_e32 v80, v81, v80
	v_add_f32_e32 v81, v187, v189
	v_add_f32_e32 v80, v81, v80
	v_add_f32_e32 v81, v170, v190
	v_add_f32_e32 v82, v81, v80
	v_add_f32_e32 v81, v177, v155
	v_add_f32_e32 v80, v176, v154
	s_waitcnt lgkmcnt(0)
	v_mfma_f32_32x32x16_bf16 v[96:111], v[192:195], v[128:131], v[96:111]
	v_add_f32_e32 v80, v80, v82
	v_add_f32_e32 v82, v81, v80
	v_add_f32_e64 v80, v174, v156
	v_add_f32_e64 v81, v175, v157
	v_add_f32_e32 v80, v80, v82
	v_add_f32_e32 v82, v81, v80
	v_add_f32_e32 v81, v181, v159
	v_add_f32_e32 v80, v180, v158
	v_add_f32_e32 v80, v80, v82
	v_add_f32_e32 v82, v81, v80
	v_add_f32_e32 v81, v179, v161
	v_add_f32_e32 v80, v178, v160
	v_add_f32_e32 v80, v80, v82
	v_add_f32_e32 v182, v81, v80
	v_cvt_pk_bf16_f32 v80, v183, v168
	v_cvt_pk_bf16_f32 v81, v185, v166
	v_cvt_pk_bf16_f32 v82, v186, v172
	v_cvt_pk_bf16_f32 v83, v187, v170
	v_cvt_pk_bf16_f32 v84, v176, v177
	v_cvt_pk_bf16_f32 v85, v174, v175
	v_cvt_pk_bf16_f32 v86, v180, v181
	v_cvt_pk_bf16_f32 v87, v178, v179
	v_cvt_pk_bf16_f32 v88, v152, v167
	v_cvt_pk_bf16_f32 v89, v169, v171
	v_cvt_pk_bf16_f32 v90, v173, v188
	v_cvt_pk_bf16_f32 v91, v189, v190
	v_cvt_pk_bf16_f32 v92, v154, v155
	v_cvt_pk_bf16_f32 v93, v156, v157
	v_cvt_pk_bf16_f32 v94, v158, v159
	v_cvt_pk_bf16_f32 v95, v160, v161
	v_mov_b32_e32 v184, v182
	v_permlane32_swap_b32_e32 v80, v82
	v_permlane32_swap_b32_e32 v81, v83
	v_permlane32_swap_b32_e32 v84, v86
	v_permlane32_swap_b32_e32 v85, v87
	v_permlane32_swap_b32_e32 v88, v90
	v_permlane32_swap_b32_e32 v89, v91
	v_permlane32_swap_b32_e32 v92, v94
	v_permlane32_swap_b32_e32 v93, v95
	v_permlane32_swap_b32_e32 v182, v184
	s_add_i32 s0, s9, 64
	s_and_b32 s0, s0, 0x7c0
	s_cmp_lt_u32 s16, 31
	s_cselect_b32 s1, s10, s18
	s_add_i32 s48, s1, s0
	v_lshl_add_u64 v[154:155], s[48:49], 0, v[144:145]
	v_mad_u64_u32 v[156:157], s[0:1], v154, s60, v[150:151]
	v_mad_i32_i24 v157, v155, s60, v157
	v_lshl_add_u64 v[154:155], s[48:49], 0, v[146:147]
	v_mov_b64_e32 v[166:167], s[70:71]
	global_load_dwordx4 v[236:239], v[156:157], off offset:3072
	v_mad_u64_u32 v[156:157], s[0:1], v154, s60, v[166:167]
	v_mad_i32_i24 v157, v155, s60, v157
	s_mov_b32 s91, s49
	v_lshl_add_u64 v[154:155], v[156:157], 0, s[90:91]
	v_lshl_add_u64 v[154:155], v[154:155], 0, v[148:149]
	v_add_co_u32_e32 v156, vcc, s58, v154
	s_nop 1
	v_addc_co_u32_e32 v157, vcc, 0, v155, vcc
	global_load_dwordx4 v[244:247], v[154:155], off
	global_load_dwordx4 v[248:251], v[156:157], off
	ds_read_b64_tr_b16 v[168:169], v206 offset:0
	ds_read_b64_tr_b16 v[170:171], v206 offset:0x800
	ds_read_b64_tr_b16 v[172:173], v206 offset:0x1000
	ds_read_b64_tr_b16 v[174:175], v206 offset:0x1800
	ds_read_b64_tr_b16 v[176:177], v206 offset:0x2000
	ds_read_b64_tr_b16 v[178:179], v206 offset:0x2800
	ds_read_b64_tr_b16 v[190:191], v206 offset:0x3000
	ds_read_b64_tr_b16 v[192:193], v206 offset:0x3800
	s_waitcnt lgkmcnt(0)
	s_nop 0
	v_mfma_f32_32x32x16_bf16 v[48:63], v[80:83], v[168:171], v[48:63]
	v_exp_f32_e32 v154, v96
	v_exp_f32_e32 v168, v97
	ds_read_b64_tr_b16 v[96:97], v206 offset:0x200
	v_exp_f32_e32 v155, v98
	v_exp_f32_e32 v170, v99
	ds_read_b64_tr_b16 v[98:99], v206 offset:0xa00
	v_mfma_f32_32x32x16_bf16 v[48:63], v[84:87], v[172:175], v[48:63]
	ds_read_b64_tr_b16 v[172:173], v206 offset:0x1200
	ds_read_b64_tr_b16 v[174:175], v206 offset:0x1a00
	v_mfma_f32_32x32x16_bf16 v[48:63], v[88:91], v[176:179], v[48:63]
	ds_read_b64_tr_b16 v[176:177], v206 offset:0x2200
	ds_read_b64_tr_b16 v[178:179], v206 offset:0x2a00
	v_mfma_f32_32x32x16_bf16 v[48:63], v[92:95], v[190:193], v[48:63]
	ds_read_b64_tr_b16 v[190:191], v206 offset:0x3200
	ds_read_b64_tr_b16 v[192:193], v206 offset:0x3a00
	s_waitcnt lgkmcnt(0)
	v_mfma_f32_32x32x16_bf16 v[32:47], v[80:83], v[96:99], v[32:47]
	s_waitcnt vmcnt(3)
	ds_write_b128 v209, v[162:165] offset:32768
	ds_write_b128 v210, v[224:227]
	ds_write_b128 v211, v[232:235]
	ds_read_b64_tr_b16 v[96:97], v206 offset:0x400
	ds_read_b64_tr_b16 v[98:99], v206 offset:0xc00
	v_exp_f32_e32 v156, v100
	v_exp_f32_e32 v157, v102
	v_mfma_f32_32x32x16_bf16 v[32:47], v[84:87], v[172:175], v[32:47]
	v_exp_f32_e32 v172, v101
	ds_read_b64_tr_b16 v[100:101], v206 offset:0x1400
	v_exp_f32_e32 v174, v103
	ds_read_b64_tr_b16 v[102:103], v206 offset:0x1c00
	v_mfma_f32_32x32x16_bf16 v[32:47], v[88:91], v[176:179], v[32:47]
	ds_read_b64_tr_b16 v[176:177], v206 offset:0x2400
	ds_read_b64_tr_b16 v[178:179], v206 offset:0x2c00
	v_mfma_f32_32x32x16_bf16 v[32:47], v[92:95], v[190:193], v[32:47]
	ds_read_b64_tr_b16 v[190:191], v206 offset:0x3400
	ds_read_b64_tr_b16 v[192:193], v206 offset:0x3c00
	v_xor_b32_e32 v207, 0x10000, v207
	v_xor_b32_e32 v208, 0x10000, v208
	v_xor_b32_e32 v213, 0x10000, v213
	v_xor_b32_e32 v212, 0x10000, v212
	s_waitcnt lgkmcnt(0)
	v_mfma_f32_32x32x16_bf16 v[16:31], v[80:83], v[96:99], v[16:31]
	ds_read_b64_tr_b16 v[96:97], v206 offset:0x600
	ds_read_b64_tr_b16 v[98:99], v206 offset:0xe00
	v_exp_f32_e32 v158, v104
	v_exp_f32_e32 v159, v106
	v_mfma_f32_32x32x16_bf16 v[16:31], v[84:87], v[100:103], v[16:31]
	ds_read_b64_tr_b16 v[100:101], v206 offset:0x1600
	ds_read_b64_tr_b16 v[102:103], v206 offset:0x1e00
	v_mfma_f32_32x32x16_bf16 v[16:31], v[88:91], v[176:179], v[16:31]
	v_exp_f32_e32 v176, v105
	ds_read_b64_tr_b16 v[104:105], v206 offset:0x2600
	v_exp_f32_e32 v178, v107
	ds_read_b64_tr_b16 v[106:107], v206 offset:0x2e00
	ds_read_b64_tr_b16 v[220:221], v206 offset:0x3600
	ds_read_b64_tr_b16 v[222:223], v206 offset:0x3e00
	s_waitcnt lgkmcnt(0)
	v_mfma_f32_32x32x16_bf16 v[16:31], v[92:95], v[190:193], v[16:31]
	v_mfma_f32_32x32x16_bf16 v[0:15], v[80:83], v[96:99], v[0:15]
	v_exp_f32_e32 v160, v108
	v_exp_f32_e32 v192, v109
	v_exp_f32_e32 v161, v110
	v_exp_f32_e32 v194, v111
	v_mfma_f32_32x32x16_bf16 v[0:15], v[84:87], v[100:103], v[0:15]
	s_waitcnt lgkmcnt(0)
	s_barrier
	v_mfma_f32_32x32x16_bf16 v[0:15], v[88:91], v[104:107], v[0:15]
	v_mfma_f32_32x32x16_bf16 v[0:15], v[92:95], v[220:223], v[0:15]
	ds_read_b128 v[186:189], v207 offset:36864
	ds_read_b128 v[80:83], v207 offset:32768
	v_exp_f32_e32 v215, v112
	v_exp_f32_e32 v152, v113
	v_exp_f32_e32 v216, v114
	v_exp_f32_e32 v217, v116
	s_waitcnt lgkmcnt(0)
	v_mfma_f32_32x32x16_bf16 v[96:111], v[80:83], v[140:143], v[64:79]
	v_add_f32_e32 v169, v154, v215
	v_add_f32_e64 v112, v168, v152
	v_add_f32_e64 v113, v169, v153
	v_add_f32_e32 v171, v155, v216
	v_add_f32_e32 v113, v112, v113
	v_exp_f32_e32 v218, v118
	v_exp_f32_e32 v200, v119
	v_add_f32_e32 v173, v156, v217
	v_mfma_f32_32x32x16_bf16 v[80:95], v[186:189], v[140:143], v[64:79]
	ds_read_b128 v[186:189], v208 offset:36864
	ds_read_b128 v[196:199], v208 offset:32768
	v_exp_f32_e32 v219, v120
	v_exp_f32_e32 v180, v121
	v_add_f32_e32 v175, v157, v218
	v_exp_f32_e32 v220, v122
	v_add_f32_e32 v177, v158, v219
	v_exp_f32_e32 v221, v124
	s_waitcnt lgkmcnt(0)
	v_mfma_f32_32x32x16_bf16 v[96:111], v[196:199], v[136:139], v[96:111]
	v_add_f32_e32 v179, v159, v220
	v_exp_f32_e32 v222, v126
	v_exp_f32_e32 v190, v127
	v_add_f32_e32 v193, v160, v221
	v_add_f32_e32 v195, v161, v222
	v_mfma_f32_32x32x16_bf16 v[80:95], v[186:189], v[136:139], v[80:95]
	ds_read_b128 v[186:189], v213 offset:36864
	ds_read_b128 v[196:199], v213 offset:32768
	s_waitcnt lgkmcnt(0)
	v_mfma_f32_32x32x16_bf16 v[96:111], v[196:199], v[132:135], v[96:111]
	v_mfma_f32_32x32x16_bf16 v[80:95], v[186:189], v[132:135], v[80:95]
	ds_read_b128 v[186:189], v212 offset:36864
	ds_read_b128 v[196:199], v212 offset:32768
	s_waitcnt lgkmcnt(0)
	v_mfma_f32_32x32x16_bf16 v[96:111], v[196:199], v[128:131], v[96:111]
	v_exp_f32_e32 v196, v115
	v_exp_f32_e32 v198, v117
	v_add_f32_e32 v113, v171, v113
	v_add_f32_e32 v112, v170, v196
	v_add_f32_e32 v113, v112, v113
	v_add_f32_e32 v113, v173, v113
	v_add_f32_e32 v112, v172, v198
	v_mfma_f32_32x32x16_bf16 v[80:95], v[186:189], v[128:131], v[80:95]
	v_add_f32_e32 v113, v112, v113
	v_add_f32_e32 v113, v175, v113
	v_add_f32_e32 v112, v174, v200
	v_exp_f32_e32 v186, v123
	v_add_f32_e32 v113, v112, v113
	v_add_f32_e32 v113, v177, v113
	v_add_f32_e32 v112, v176, v180
	v_exp_f32_e32 v188, v125
	v_add_f32_e32 v113, v112, v113
	v_add_f32_e32 v113, v179, v113
	v_add_f32_e32 v112, v178, v186
	v_add_f32_e32 v113, v112, v113
	v_add_f32_e32 v113, v193, v113
	v_add_f32_e32 v112, v192, v188
	v_add_f32_e32 v113, v112, v113
	v_add_f32_e32 v113, v195, v113
	v_add_f32_e32 v112, v194, v190
	v_add_f32_e32 v112, v112, v113
	v_mov_b32_e32 v113, v112
	v_mov_b32_e32 v185, v112
	s_nop 1
	v_permlane32_swap_b32_e32 v112, v185
	v_mov_b32_e32 v183, v112
	v_add_f32_e32 v113, v183, v185
	v_add_f32_e32 v112, v182, v184
	v_cmp_ngt_f32_e32 vcc, s59, v113
	v_cmp_ngt_f32_e64 s[0:1], s59, v112
	v_fma_f32 v114, v204, v214, v112
	s_or_b64 s[0:1], s[0:1], vcc
	v_add_f32_e32 v204, v114, v113
	s_or_b64 s[14:15], s[14:15], s[0:1]
	v_cvt_pk_bf16_f32 v112, v154, v168
	v_cvt_pk_bf16_f32 v113, v155, v170
	v_cvt_pk_bf16_f32 v114, v156, v172
	v_cvt_pk_bf16_f32 v115, v157, v174
	v_cvt_pk_bf16_f32 v116, v158, v176
	v_cvt_pk_bf16_f32 v117, v159, v178
	v_cvt_pk_bf16_f32 v118, v160, v192
	v_cvt_pk_bf16_f32 v119, v161, v194
	v_cvt_pk_bf16_f32 v120, v215, v152
	v_cvt_pk_bf16_f32 v121, v216, v196
	v_cvt_pk_bf16_f32 v122, v217, v198
	v_cvt_pk_bf16_f32 v123, v218, v200
	v_cvt_pk_bf16_f32 v124, v219, v180
	v_cvt_pk_bf16_f32 v125, v220, v186
	v_cvt_pk_bf16_f32 v126, v221, v188
	v_cvt_pk_bf16_f32 v127, v222, v190
	s_nop 0
	v_permlane32_swap_b32_e32 v112, v114
	v_permlane32_swap_b32_e32 v113, v115
	v_permlane32_swap_b32_e32 v116, v118
	v_permlane32_swap_b32_e32 v117, v119
	v_permlane32_swap_b32_e32 v120, v122
	v_permlane32_swap_b32_e32 v121, v123
	v_permlane32_swap_b32_e32 v124, v126
	v_permlane32_swap_b32_e32 v125, v127
	s_add_i32 s0, s16, -1
	s_cmp_lt_u32 s16, 30
	s_cselect_b32 s1, 0, 0xffffffe0
	s_cselect_b32 s17, s10, s18
	s_add_i32 s1, s1, s16
	s_lshl_b32 s1, s1, 6
	s_add_i32 s1, s1, s17
	s_add_i32 s48, s1, 0x80
	v_lshl_add_u64 v[154:155], s[48:49], 0, v[144:145]
	v_mad_u64_u32 v[156:157], s[22:23], v154, s60, v[150:151]
	v_mad_i32_i24 v157, v155, s60, v157
	v_lshl_add_u64 v[154:155], s[48:49], 0, v[146:147]
	global_load_dwordx4 v[162:165], v[156:157], off offset:3072
	v_mad_u64_u32 v[156:157], s[22:23], v154, s60, v[166:167]
	v_mad_i32_i24 v157, v155, s60, v157
	v_lshl_add_u64 v[154:155], v[156:157], 0, s[90:91]
	v_lshl_add_u64 v[154:155], v[154:155], 0, v[148:149]
	v_add_co_u32_e32 v156, vcc, s58, v154
	s_nop 1
	v_addc_co_u32_e32 v157, vcc, 0, v155, vcc
	global_load_dwordx4 v[224:227], v[154:155], off
	global_load_dwordx4 v[232:235], v[156:157], off
	ds_read_b64_tr_b16 v[166:167], v205 offset:0
	ds_read_b64_tr_b16 v[168:169], v205 offset:0x800
	ds_read_b64_tr_b16 v[170:171], v205 offset:0x1000
	ds_read_b64_tr_b16 v[172:173], v205 offset:0x1800
	ds_read_b64_tr_b16 v[174:175], v205 offset:0x2000
	ds_read_b64_tr_b16 v[176:177], v205 offset:0x2800
	ds_read_b64_tr_b16 v[178:179], v205 offset:0x3000
	ds_read_b64_tr_b16 v[180:181], v205 offset:0x3800
	s_waitcnt lgkmcnt(0)
	s_nop 0
	v_mfma_f32_32x32x16_bf16 v[48:63], v[112:115], v[166:169], v[48:63]
	v_exp_f32_e32 v183, v96
	v_exp_f32_e32 v168, v97
	ds_read_b64_tr_b16 v[96:97], v205 offset:0x200
	v_exp_f32_e32 v185, v98
	v_exp_f32_e32 v166, v99
	ds_read_b64_tr_b16 v[98:99], v205 offset:0xa00
	v_mfma_f32_32x32x16_bf16 v[48:63], v[116:119], v[170:173], v[48:63]
	ds_read_b64_tr_b16 v[170:171], v205 offset:0x1200
	ds_read_b64_tr_b16 v[172:173], v205 offset:0x1a00
	v_mfma_f32_32x32x16_bf16 v[48:63], v[120:123], v[174:177], v[48:63]
	ds_read_b64_tr_b16 v[174:175], v205 offset:0x2200
	ds_read_b64_tr_b16 v[176:177], v205 offset:0x2a00
	v_mfma_f32_32x32x16_bf16 v[48:63], v[124:127], v[178:181], v[48:63]
	ds_read_b64_tr_b16 v[178:179], v205 offset:0x3200
	ds_read_b64_tr_b16 v[180:181], v205 offset:0x3a00
	s_waitcnt lgkmcnt(0)
	v_mfma_f32_32x32x16_bf16 v[32:47], v[112:115], v[96:99], v[32:47]
	s_waitcnt vmcnt(3)
	ds_write_b128 v209, v[236:239] offset:40960
	ds_write_b128 v210, v[244:247] offset:16384
	ds_write_b128 v211, v[248:251] offset:16384
	ds_read_b64_tr_b16 v[96:97], v205 offset:0x400
	ds_read_b64_tr_b16 v[98:99], v205 offset:0xc00
	v_exp_f32_e32 v186, v100
	v_exp_f32_e32 v187, v102
	v_mfma_f32_32x32x16_bf16 v[32:47], v[116:119], v[170:173], v[32:47]
	v_exp_f32_e32 v172, v101
	ds_read_b64_tr_b16 v[100:101], v205 offset:0x1400
	v_exp_f32_e32 v170, v103
	ds_read_b64_tr_b16 v[102:103], v205 offset:0x1c00
	v_mfma_f32_32x32x16_bf16 v[32:47], v[120:123], v[174:177], v[32:47]
	ds_read_b64_tr_b16 v[174:175], v205 offset:0x2400
	ds_read_b64_tr_b16 v[176:177], v205 offset:0x2c00
	v_mfma_f32_32x32x16_bf16 v[32:47], v[124:127], v[178:181], v[32:47]
	ds_read_b64_tr_b16 v[178:179], v205 offset:0x3400
	ds_read_b64_tr_b16 v[180:181], v205 offset:0x3c00
	v_xor_b32_e32 v206, 0x10000, v206
	s_waitcnt lgkmcnt(0)
	v_mfma_f32_32x32x16_bf16 v[16:31], v[112:115], v[96:99], v[16:31]
	ds_read_b64_tr_b16 v[96:97], v205 offset:0x600
	ds_read_b64_tr_b16 v[98:99], v205 offset:0xe00
	v_mfma_f32_32x32x16_bf16 v[16:31], v[116:119], v[100:103], v[16:31]
	ds_read_b64_tr_b16 v[100:101], v205 offset:0x1600
	ds_read_b64_tr_b16 v[102:103], v205 offset:0x1e00
	v_mfma_f32_32x32x16_bf16 v[16:31], v[120:123], v[174:177], v[16:31]
	v_exp_f32_e32 v176, v104
	v_exp_f32_e32 v177, v105
	ds_read_b64_tr_b16 v[104:105], v205 offset:0x2600
	v_exp_f32_e32 v174, v106
	v_exp_f32_e32 v175, v107
	ds_read_b64_tr_b16 v[106:107], v205 offset:0x2e00
	ds_read_b64_tr_b16 v[214:215], v205 offset:0x3600
	v_mfma_f32_32x32x16_bf16 v[16:31], v[124:127], v[178:181], v[16:31]
	ds_read_b64_tr_b16 v[216:217], v205 offset:0x3e00
	s_waitcnt lgkmcnt(0)
	v_mfma_f32_32x32x16_bf16 v[0:15], v[112:115], v[96:99], v[0:15]
	v_exp_f32_e32 v180, v108
	v_exp_f32_e32 v181, v109
	v_exp_f32_e32 v178, v110
	v_exp_f32_e32 v179, v111
	s_andn2_b64 s[2:3], s[2:3], exec
	s_and_b64 s[22:23], s[14:15], exec
	s_addk_i32 s9, 0x80
	v_mfma_f32_32x32x16_bf16 v[0:15], v[116:119], v[100:103], v[0:15]
	s_add_i32 s16, s16, 2
	s_or_b64 s[2:3], s[2:3], s[22:23]
	s_cmp_gt_u32 s0, 32
	v_xor_b32_e32 v205, 0x10000, v205
	v_xor_b32_e32 v209, 0x10000, v209
	v_xor_b32_e32 v210, 0x10000, v210
	v_xor_b32_e32 v211, 0x10000, v211
	v_mfma_f32_32x32x16_bf16 v[0:15], v[120:123], v[104:107], v[0:15]
	s_waitcnt lgkmcnt(0)
	s_barrier
	v_mfma_f32_32x32x16_bf16 v[0:15], v[124:127], v[214:217], v[0:15]
	v_mov_b32_e32 v214, 1.0
	s_cbranch_scc0 .LBB0_797
	v_mov_b32_e32 v239, s100
	ds_read_b128 v[112:115], v207 offset:45056
	ds_read_b128 v[116:119], v207 offset:40960
	v_exp_f32_e32 v152, v81
	v_exp_f32_e32 v124, v84
	v_exp_f32_e32 v84, v85
	v_exp_f32_e32 v125, v86
	s_waitcnt lgkmcnt(0)
	v_mfma_f32_32x32x16_bf16 v[96:111], v[116:119], v[140:143], v[64:79]
	v_exp_f32_e32 v86, v87
	v_add_f32_e32 v173, v186, v124
	v_exp_f32_e32 v126, v88
	v_add_f32_e32 v171, v187, v125
	v_exp_f32_e32 v127, v90
	v_exp_f32_e32 v120, v93
	v_exp_f32_e32 v122, v95
	v_mfma_f32_32x32x16_bf16 v[64:79], v[112:115], v[140:143], v[64:79]
	ds_read_b128 v[112:115], v208 offset:45056
	ds_read_b128 v[116:119], v208 offset:40960
	s_waitcnt lgkmcnt(1)
	v_mfma_f32_32x32x16_bf16 v[64:79], v[112:115], v[136:139], v[64:79]
	s_waitcnt lgkmcnt(0)
	v_mfma_f32_32x32x16_bf16 v[96:111], v[116:119], v[136:139], v[96:111]
	ds_read_b128 v[112:115], v213 offset:45056
	ds_read_b128 v[116:119], v213 offset:40960
	s_waitcnt lgkmcnt(1)
	v_mfma_f32_32x32x16_bf16 v[64:79], v[112:115], v[132:135], v[64:79]
	s_waitcnt lgkmcnt(0)
	v_mfma_f32_32x32x16_bf16 v[96:111], v[116:119], v[132:135], v[96:111]
	ds_read_b128 v[112:115], v212 offset:45056
	ds_read_b128 v[116:119], v212 offset:40960
	v_cvt_pk_bf16_f32 v88, v183, v168
	s_waitcnt lgkmcnt(1)
	v_mfma_f32_32x32x16_bf16 v[64:79], v[112:115], v[128:131], v[64:79]
	v_exp_f32_e32 v112, v80
	v_exp_f32_e32 v113, v82
	v_exp_f32_e32 v114, v83
	v_add_f32_e32 v83, v176, v126
	v_add_f32_e32 v169, v183, v112
	v_pk_add_f32 v[80:81], v[168:169], v[152:153]
	v_add_f32_e32 v167, v185, v113
	v_pk_add_f32 v[80:81], v[80:81], v[80:81] op_sel_hi:[0,1]
	v_mov_b32_e32 v115, v81
	v_pk_add_f32 v[80:81], v[166:167], v[114:115]
	s_waitcnt lgkmcnt(0)
	v_mfma_f32_32x32x16_bf16 v[96:111], v[116:119], v[128:131], v[96:111]
	v_pk_add_f32 v[80:81], v[80:81], v[80:81] op_sel_hi:[0,1]
	v_mov_b32_e32 v85, v81
	v_pk_add_f32 v[80:81], v[172:173], v[84:85]
	v_exp_f32_e32 v116, v89
	v_pk_add_f32 v[80:81], v[80:81], v[80:81] op_sel_hi:[0,1]
	v_mov_b32_e32 v87, v81
	v_pk_add_f32 v[80:81], v[170:171], v[86:87]
	v_exp_f32_e32 v118, v91
	v_pk_add_f32 v[80:81], v[80:81], v[80:81] op_sel_hi:[0,1]
	v_mov_b32_e32 v82, v177
	v_mov_b32_e32 v117, v81
	v_pk_add_f32 v[80:81], v[82:83], v[116:117]
	v_exp_f32_e32 v128, v92
	v_pk_add_f32 v[80:81], v[80:81], v[80:81] op_sel_hi:[0,1]
	v_add_f32_e32 v83, v174, v127
	v_mov_b32_e32 v82, v175
	v_mov_b32_e32 v119, v81
	v_pk_add_f32 v[80:81], v[82:83], v[118:119]
	v_exp_f32_e32 v129, v94
	v_pk_add_f32 v[80:81], v[80:81], v[80:81] op_sel_hi:[0,1]
	v_add_f32_e32 v83, v180, v128
	v_mov_b32_e32 v82, v181
	v_mov_b32_e32 v121, v81
	v_pk_add_f32 v[80:81], v[82:83], v[120:121]
	v_add_f32_e32 v83, v178, v129
	v_pk_add_f32 v[80:81], v[80:81], v[80:81] op_sel_hi:[0,1]
	v_mov_b32_e32 v82, v179
	v_mov_b32_e32 v123, v81
	v_pk_add_f32 v[80:81], v[82:83], v[122:123]
	v_cvt_pk_bf16_f32 v89, v185, v166
	v_cvt_pk_bf16_f32 v90, v186, v172
	v_cvt_pk_bf16_f32 v91, v187, v170
	v_cvt_pk_bf16_f32 v92, v176, v177
	v_cvt_pk_bf16_f32 v93, v174, v175
	s_nop 0
	v_pk_add_f32 v[80:81], v[80:81], v[80:81] op_sel:[0,1] op_sel_hi:[1,0]
	v_cvt_pk_bf16_f32 v94, v180, v181
	v_cvt_pk_bf16_f32 v95, v178, v179
	v_cvt_pk_bf16_f32 v112, v112, v152
	v_cvt_pk_bf16_f32 v113, v113, v114
	v_cvt_pk_bf16_f32 v114, v124, v84
	s_nop 0
	v_mov_b32_e32 v82, v80
	v_cvt_pk_bf16_f32 v115, v125, v86
	v_cvt_pk_bf16_f32 v116, v126, v116
	v_cvt_pk_bf16_f32 v117, v127, v118
	v_cvt_pk_bf16_f32 v118, v128, v120
	v_cvt_pk_bf16_f32 v119, v129, v122
	s_nop 1
	v_permlane32_swap_b32_e32 v80, v82
	v_permlane32_swap_b32_e32 v88, v90
	v_permlane32_swap_b32_e32 v89, v91
	v_permlane32_swap_b32_e32 v92, v94
	v_permlane32_swap_b32_e32 v93, v95
	v_permlane32_swap_b32_e32 v112, v114
	v_permlane32_swap_b32_e32 v113, v115
	v_permlane32_swap_b32_e32 v116, v118
	v_permlane32_swap_b32_e32 v117, v119
	ds_read_b64_tr_b16 v[84:85], v206 offset:0
	ds_read_b64_tr_b16 v[86:87], v206 offset:0x800
	ds_read_b64_tr_b16 v[120:121], v206 offset:0x1000
	ds_read_b64_tr_b16 v[122:123], v206 offset:0x1800
	ds_read_b64_tr_b16 v[124:125], v206 offset:0x2000
	ds_read_b64_tr_b16 v[126:127], v206 offset:0x2800
	ds_read_b64_tr_b16 v[128:129], v206 offset:0x3000
	ds_read_b64_tr_b16 v[130:131], v206 offset:0x3800
	s_waitcnt lgkmcnt(0)
	s_nop 0
	v_mfma_f32_32x32x16_bf16 v[48:63], v[88:91], v[84:87], v[48:63]
	v_exp_f32_e32 v132, v96
	v_exp_f32_e32 v84, v97
	ds_read_b64_tr_b16 v[96:97], v206 offset:0x200
	v_exp_f32_e32 v133, v98
	v_exp_f32_e32 v86, v99
	ds_read_b64_tr_b16 v[98:99], v206 offset:0xa00
	v_mfma_f32_32x32x16_bf16 v[48:63], v[92:95], v[120:123], v[48:63]
	ds_read_b64_tr_b16 v[120:121], v206 offset:0x1200
	ds_read_b64_tr_b16 v[122:123], v206 offset:0x1a00
	v_mfma_f32_32x32x16_bf16 v[48:63], v[112:115], v[124:127], v[48:63]
	ds_read_b64_tr_b16 v[124:125], v206 offset:0x2200
	ds_read_b64_tr_b16 v[126:127], v206 offset:0x2a00
	v_mfma_f32_32x32x16_bf16 v[48:63], v[116:119], v[128:131], v[48:63]
	ds_read_b64_tr_b16 v[128:129], v206 offset:0x3200
	ds_read_b64_tr_b16 v[130:131], v206 offset:0x3a00
	s_waitcnt lgkmcnt(0)
	v_mfma_f32_32x32x16_bf16 v[32:47], v[88:91], v[96:99], v[32:47]
	ds_read_b64_tr_b16 v[96:97], v206 offset:0x400
	ds_read_b64_tr_b16 v[98:99], v206 offset:0xc00
	v_exp_f32_e32 v134, v100
	v_exp_f32_e32 v135, v102
	v_mfma_f32_32x32x16_bf16 v[32:47], v[92:95], v[120:123], v[32:47]
	v_mfma_f32_32x32x16_bf16 v[32:47], v[112:115], v[124:127], v[32:47]
	v_mfma_f32_32x32x16_bf16 v[32:47], v[116:119], v[128:131], v[32:47]
	v_exp_f32_e32 v128, v101
	ds_read_b64_tr_b16 v[100:101], v206 offset:0x1400
	v_exp_f32_e32 v130, v103
	ds_read_b64_tr_b16 v[102:103], v206 offset:0x1c00
	ds_read_b64_tr_b16 v[120:121], v206 offset:0x2400
	ds_read_b64_tr_b16 v[122:123], v206 offset:0x2c00
	ds_read_b64_tr_b16 v[124:125], v206 offset:0x3400
	ds_read_b64_tr_b16 v[126:127], v206 offset:0x3c00
	s_waitcnt lgkmcnt(0)
	v_mfma_f32_32x32x16_bf16 v[16:31], v[88:91], v[96:99], v[16:31]
	ds_read_b64_tr_b16 v[96:97], v206 offset:0x600
	ds_read_b64_tr_b16 v[98:99], v206 offset:0xe00
	v_exp_f32_e32 v136, v104
	v_exp_f32_e32 v137, v106
	v_mfma_f32_32x32x16_bf16 v[16:31], v[92:95], v[100:103], v[16:31]
	ds_read_b64_tr_b16 v[100:101], v206 offset:0x1600
	ds_read_b64_tr_b16 v[102:103], v206 offset:0x1e00
	v_mfma_f32_32x32x16_bf16 v[16:31], v[112:115], v[120:123], v[16:31]
	v_mfma_f32_32x32x16_bf16 v[16:31], v[116:119], v[124:127], v[16:31]
	v_exp_f32_e32 v124, v105
	ds_read_b64_tr_b16 v[104:105], v206 offset:0x2600
	v_exp_f32_e32 v126, v107
	ds_read_b64_tr_b16 v[106:107], v206 offset:0x2e00
	ds_read_b64_tr_b16 v[120:121], v206 offset:0x3600
	ds_read_b64_tr_b16 v[122:123], v206 offset:0x3e00
	s_waitcnt lgkmcnt(0)
	v_mfma_f32_32x32x16_bf16 v[0:15], v[88:91], v[96:99], v[0:15]
	v_exp_f32_e32 v152, v65
	v_exp_f32_e32 v88, v109
	v_exp_f32_e32 v109, v66
	v_exp_f32_e32 v90, v111
	v_exp_f32_e32 v111, v70
	v_exp_f32_e32 v96, v71
	v_add_f32_e32 v87, v133, v109
	v_mfma_f32_32x32x16_bf16 v[0:15], v[92:95], v[100:103], v[0:15]
	v_exp_f32_e32 v92, v67
	v_exp_f32_e32 v94, v69
	v_exp_f32_e32 v98, v73
	v_add_f32_e32 v131, v135, v111
	v_exp_f32_e32 v100, v75
	v_exp_f32_e32 v102, v77
	v_cvt_pk_bf16_f32 v66, v132, v84
	v_mfma_f32_32x32x16_bf16 v[0:15], v[112:115], v[104:107], v[0:15]
	v_exp_f32_e32 v106, v108
	v_exp_f32_e32 v108, v64
	v_exp_f32_e32 v107, v110
	v_exp_f32_e32 v110, v68
	v_exp_f32_e32 v112, v72
	v_add_f32_e32 v85, v132, v108
	v_pk_add_f32 v[64:65], v[84:85], v[152:153]
	v_add_f32_e32 v129, v134, v110
	v_pk_add_f32 v[64:65], v[64:65], v[64:65] op_sel_hi:[0,1]
	v_mov_b32_e32 v93, v65
	v_pk_add_f32 v[64:65], v[86:87], v[92:93]
	v_exp_f32_e32 v113, v74
	v_pk_add_f32 v[64:65], v[64:65], v[64:65] op_sel_hi:[0,1]
	v_mov_b32_e32 v95, v65
	v_pk_add_f32 v[64:65], v[128:129], v[94:95]
	v_add_f32_e32 v125, v136, v112
	v_pk_add_f32 v[64:65], v[64:65], v[64:65] op_sel_hi:[0,1]
	v_mov_b32_e32 v97, v65
	v_pk_add_f32 v[64:65], v[130:131], v[96:97]
	v_exp_f32_e32 v114, v76
	v_pk_add_f32 v[64:65], v[64:65], v[64:65] op_sel_hi:[0,1]
	v_mov_b32_e32 v99, v65
	v_pk_add_f32 v[64:65], v[124:125], v[98:99]
	v_add_f32_e32 v127, v137, v113
	v_pk_add_f32 v[64:65], v[64:65], v[64:65] op_sel_hi:[0,1]
	v_mov_b32_e32 v101, v65
	v_pk_add_f32 v[64:65], v[126:127], v[100:101]
	v_exp_f32_e32 v115, v78
	v_pk_add_f32 v[64:65], v[64:65], v[64:65] op_sel_hi:[0,1]
	v_exp_f32_e32 v104, v79
	v_add_f32_e32 v89, v106, v114
	v_mov_b32_e32 v103, v65
	v_pk_add_f32 v[64:65], v[88:89], v[102:103]
	v_add_f32_e32 v91, v107, v115
	v_pk_add_f32 v[64:65], v[64:65], v[64:65] op_sel_hi:[0,1]
	v_mov_b32_e32 v105, v65
	v_pk_add_f32 v[64:65], v[90:91], v[104:105]
	v_mfma_f32_32x32x16_bf16 v[0:15], v[116:119], v[120:123], v[0:15]
	v_pk_add_f32 v[64:65], v[64:65], v[64:65] op_sel:[0,1] op_sel_hi:[1,0]
	v_cvt_pk_bf16_f32 v67, v133, v86
	v_cvt_pk_bf16_f32 v68, v134, v128
	v_cvt_pk_bf16_f32 v69, v135, v130
	v_cvt_pk_bf16_f32 v70, v136, v124
	v_cvt_pk_bf16_f32 v71, v137, v126
	s_nop 0
	v_mov_b32_e32 v83, v64
	s_nop 1
	v_permlane32_swap_b32_e32 v64, v83
	v_mov_b32_e32 v81, v64
	v_pk_add_f32 v[64:65], v[80:81], v[82:83]
	v_cvt_pk_bf16_f32 v72, v106, v88
	v_cvt_pk_bf16_f32 v73, v107, v90
	v_cvt_pk_bf16_f32 v74, v108, v152
	v_cvt_pk_bf16_f32 v75, v109, v92
	v_cvt_pk_bf16_f32 v76, v110, v94
	s_nop 0
	v_cmp_ngt_f32_e32 vcc, s59, v65
	v_cmp_ngt_f32_e64 s[0:1], s59, v64
	s_or_b64 s[0:1], s[0:1], vcc
	s_or_b64 s[0:1], s[2:3], s[0:1]
	v_cvt_pk_bf16_f32 v77, v111, v96
	v_cvt_pk_bf16_f32 v78, v112, v98
	v_cvt_pk_bf16_f32 v79, v113, v100
	v_cvt_pk_bf16_f32 v80, v114, v102
	v_cvt_pk_bf16_f32 v81, v115, v104
	v_permlane32_swap_b32_e32 v66, v68
	v_permlane32_swap_b32_e32 v67, v69
	v_permlane32_swap_b32_e32 v70, v72
	v_permlane32_swap_b32_e32 v71, v73
	v_permlane32_swap_b32_e32 v74, v76
	v_permlane32_swap_b32_e32 v75, v77
	v_permlane32_swap_b32_e32 v78, v80
	v_permlane32_swap_b32_e32 v79, v81
	ds_read_b64_tr_b16 v[82:83], v205 offset:0
	ds_read_b64_tr_b16 v[84:85], v205 offset:0x800
	ds_read_b64_tr_b16 v[86:87], v205 offset:0x1000
	ds_read_b64_tr_b16 v[88:89], v205 offset:0x1800
	ds_read_b64_tr_b16 v[90:91], v205 offset:0x2000
	ds_read_b64_tr_b16 v[92:93], v205 offset:0x2800
	ds_read_b64_tr_b16 v[94:95], v205 offset:0x3000
	ds_read_b64_tr_b16 v[96:97], v205 offset:0x3800
	s_waitcnt lgkmcnt(0)
	s_nop 0
	v_mfma_f32_32x32x16_bf16 v[48:63], v[66:69], v[82:85], v[48:63]
	ds_read_b64_tr_b16 v[82:83], v205 offset:0x200
	ds_read_b64_tr_b16 v[84:85], v205 offset:0xa00
	v_mfma_f32_32x32x16_bf16 v[48:63], v[70:73], v[86:89], v[48:63]
	ds_read_b64_tr_b16 v[86:87], v205 offset:0x1200
	ds_read_b64_tr_b16 v[88:89], v205 offset:0x1a00
	v_mfma_f32_32x32x16_bf16 v[48:63], v[74:77], v[90:93], v[48:63]
	ds_read_b64_tr_b16 v[90:91], v205 offset:0x2200
	ds_read_b64_tr_b16 v[92:93], v205 offset:0x2a00
	v_mfma_f32_32x32x16_bf16 v[48:63], v[78:81], v[94:97], v[48:63]
	ds_read_b64_tr_b16 v[94:95], v205 offset:0x3200
	ds_read_b64_tr_b16 v[96:97], v205 offset:0x3a00
	s_waitcnt lgkmcnt(0)
	v_mfma_f32_32x32x16_bf16 v[32:47], v[66:69], v[82:85], v[32:47]
	ds_read_b64_tr_b16 v[82:83], v205 offset:0x400
	ds_read_b64_tr_b16 v[84:85], v205 offset:0xc00
	v_mfma_f32_32x32x16_bf16 v[32:47], v[70:73], v[86:89], v[32:47]
	ds_read_b64_tr_b16 v[86:87], v205 offset:0x1400
	ds_read_b64_tr_b16 v[88:89], v205 offset:0x1c00
	v_mfma_f32_32x32x16_bf16 v[32:47], v[74:77], v[90:93], v[32:47]
	ds_read_b64_tr_b16 v[90:91], v205 offset:0x2400
	ds_read_b64_tr_b16 v[92:93], v205 offset:0x2c00
	v_mfma_f32_32x32x16_bf16 v[32:47], v[78:81], v[94:97], v[32:47]
	ds_read_b64_tr_b16 v[94:95], v205 offset:0x3400
	ds_read_b64_tr_b16 v[96:97], v205 offset:0x3c00
	s_waitcnt lgkmcnt(0)
	v_mfma_f32_32x32x16_bf16 v[16:31], v[66:69], v[82:85], v[16:31]
	ds_read_b64_tr_b16 v[82:83], v205 offset:0x600
	ds_read_b64_tr_b16 v[84:85], v205 offset:0xe00
	v_mfma_f32_32x32x16_bf16 v[16:31], v[70:73], v[86:89], v[16:31]
	ds_read_b64_tr_b16 v[86:87], v205 offset:0x1600
	ds_read_b64_tr_b16 v[88:89], v205 offset:0x1e00
	v_mfma_f32_32x32x16_bf16 v[16:31], v[74:77], v[90:93], v[16:31]
	ds_read_b64_tr_b16 v[90:91], v205 offset:0x2600
	ds_read_b64_tr_b16 v[92:93], v205 offset:0x2e00
	v_mfma_f32_32x32x16_bf16 v[16:31], v[78:81], v[94:97], v[16:31]
	ds_read_b64_tr_b16 v[94:95], v205 offset:0x3600
	ds_read_b64_tr_b16 v[96:97], v205 offset:0x3e00
	s_waitcnt lgkmcnt(0)
	v_mfma_f32_32x32x16_bf16 v[0:15], v[66:69], v[82:85], v[0:15]
	v_mfma_f32_32x32x16_bf16 v[0:15], v[70:73], v[86:89], v[0:15]
	v_mfma_f32_32x32x16_bf16 v[0:15], v[74:77], v[90:93], v[0:15]
	v_mfma_f32_32x32x16_bf16 v[0:15], v[78:81], v[94:97], v[0:15]
	s_setprio 0
	v_and_b32_e32 v205, 0xfffeffff, v205
	v_and_b32_e32 v206, 0xfffeffff, v206
	v_and_b32_e32 v207, 0xfffeffff, v207
	v_and_b32_e32 v208, 0xfffeffff, v208
	v_and_b32_e32 v209, 0xfffeffff, v209
	v_and_b32_e32 v210, 0xfffeffff, v210
	v_and_b32_e32 v211, 0xfffeffff, v211
	v_and_b32_e32 v212, 0xfffeffff, v212
	v_and_b32_e32 v213, 0xfffeffff, v213
	v_cndmask_b32_e64 v66, 0, 1, s[0:1]
	v_cmp_ne_u32_e32 vcc, 0, v66
	s_cmp_lg_u64 vcc, 0
	s_cselect_b64 s[0:1], -1, 0
	v_cmp_eq_u32_e32 vcc, 0, v203
	s_and_b64 s[2:3], vcc, s[0:1]
	s_and_saveexec_b64 s[0:1], s[2:3]
	ds_write_b32 v153, v229 offset:51200
	s_or_b64 exec, exec, s[0:1]
	s_waitcnt vmcnt(0) lgkmcnt(0)
	s_barrier
	ds_read_b32 v66, v153 offset:51200
	s_mov_b32 s9, s49
	s_waitcnt lgkmcnt(0)
	s_barrier
	v_cmp_eq_u32_e32 vcc, 0, v66
	s_cbranch_vccnz .LBB0_824
	v_mbcnt_lo_u32_b32 v0, -1, 0
	v_mbcnt_hi_u32_b32 v0, -1, v0
	v_mov_b64_e32 v[14:15], s[94:95]
	v_add_u32_e32 v35, s33, v0
	v_mov_b32_e32 v33, v153
	v_ashrrev_i32_e32 v0, 1, v35
	v_and_b32_e32 v34, 31, v35
	v_and_b32_e32 v0, 0xffffffe0, v0
	v_ashrrev_i32_e32 v1, 31, v0
	v_or_b32_e32 v152, s8, v34
	v_ashrrev_i32_e32 v148, 3, v35
	v_lshlrev_b32_e32 v16, 3, v35
	v_lshl_add_u64 v[12:13], v[152:153], 0, v[0:1]
	v_and_b32_e32 v0, 56, v16
	v_ashrrev_i32_e32 v149, 31, v148
	v_lshlrev_b32_e32 v32, 1, v0
	v_lshl_add_u64 v[0:1], v[148:149], 0, s[10:11]
	v_ashrrev_i32_e32 v150, 4, v35
	v_mad_u64_u32 v[2:3], s[0:1], v0, s60, v[14:15]
	v_mad_i32_i24 v3, v1, s60, v3
	v_ashrrev_i32_e32 v151, 31, v150
	v_lshl_add_u64 v[0:1], v[2:3], 0, v[32:33]
	v_lshl_add_u64 v[2:3], v[150:151], 0, s[10:11]
	v_mov_b64_e32 v[4:5], s[70:71]
	v_mad_u64_u32 v[4:5], s[0:1], v2, s60, v[4:5]
	v_and_b32_e32 v6, 0x78, v16
	v_mad_i32_i24 v5, v3, s60, v5
	s_mov_b32 s91, s49
	v_lshl_add_u64 v[2:3], v[4:5], 0, s[90:91]
	v_lshlrev_b32_e32 v152, 1, v6
	v_lshl_add_u64 v[8:9], v[2:3], 0, v[152:153]
	global_load_dwordx4 v[0:3], v[0:1], off offset:3072
	s_nop 0
	global_load_dwordx4 v[4:7], v[8:9], off
	v_add_co_u32_e32 v8, vcc, s58, v8
	v_mad_u64_u32 v[14:15], s[0:1], v12, s60, v[14:15]
	s_nop 0
	v_addc_co_u32_e32 v9, vcc, 0, v9, vcc
	global_load_dwordx4 v[8:11], v[8:9], off
	v_lshrrev_b32_e32 v17, 1, v35
	v_mad_i32_i24 v15, v13, s60, v15
	v_and_b32_e32 v146, 16, v17
	v_mov_b32_e32 v147, v153
	v_lshl_add_u64 v[12:13], v[14:15], 0, v[146:147]
	global_load_dwordx4 v[116:119], v[12:13], off offset:2048
	global_load_dwordx4 v[120:123], v[12:13], off offset:2080
	global_load_dwordx4 v[124:127], v[12:13], off offset:2112
	global_load_dwordx4 v[112:115], v[12:13], off offset:2144
	v_and_b32_e32 v19, 0xfffff0, v150
	v_lshlrev_b32_e32 v20, 1, v150
	v_lshrrev_b32_e32 v21, 1, v150
	v_and_b32_e32 v23, 3, v150
	v_add_u32_e32 v24, 32, v150
	v_and_b32_e32 v14, 0x70, v35
	v_lshlrev_b32_e32 v18, 7, v148
	v_bfe_u32 v22, v16, 5, 2
	v_and_b32_e32 v33, 0x70, v16
	v_and_or_b32 v16, v20, 8, v19
	v_and_or_b32 v19, v21, 4, v23
	v_and_b32_e32 v20, 0xfffff0, v24
	v_lshlrev_b32_e32 v21, 1, v24
	v_lshl_add_u32 v40, v34, 7, 0
	v_bitop3_b32 v17, v17, v33, 16 bitop3:0x6c
	v_bitop3_b32 v14, v32, v18, v14 bitop3:0xde
	v_lshrrev_b32_e32 v16, 1, v16
	v_lshlrev_b32_e32 v18, 6, v19
	v_and_or_b32 v19, v21, 8, v20
	v_add_u32_e32 v171, v40, v17
	v_or_b32_e32 v16, v16, v22
	v_lshrrev_b32_e32 v17, 1, v19
	v_lshlrev_b32_e32 v15, 4, v35
	v_add_u32_e32 v172, 0, v14
	v_lshlrev_b32_e32 v14, 9, v16
	v_or_b32_e32 v16, v17, v22
	v_and_b32_e32 v15, 48, v15
	v_lshlrev_b32_e32 v12, 9, v16
	v_or3_b32 v14, v14, v18, v15
	v_or3_b32 v12, v12, v18, v15
	v_add_u32_e32 v173, 0, v14
	v_add_u32_e32 v174, 0, v12
	v_bitop3_b32 v20, v146, v33, 32 bitop3:0x36
	v_add_u32_e32 v175, v40, v20
	v_bitop3_b32 v41, v146, v33, 64 bitop3:0x36
	v_add_u32_e32 v176, v40, v41
	v_bitop3_b32 v33, v146, v33, s88 bitop3:0x36
	v_add_u32_e32 v177, v40, v33
	s_waitcnt vmcnt(6)
	ds_write_b128 v172, v[0:3] offset:32768
	s_waitcnt vmcnt(5)
	ds_write_b128 v173, v[4:7]
	s_waitcnt vmcnt(4)
	ds_write_b128 v174, v[8:11]
	s_waitcnt lgkmcnt(0)
	s_barrier
	ds_read_b128 v[0:3], v171 offset:32768
	ds_read_b128 v[16:19], v171 offset:36864
	ds_read_b128 v[36:39], v175 offset:32768
	s_waitcnt vmcnt(3) lgkmcnt(2)
	v_mfma_f32_32x32x16_bf16 v[0:15], v[0:3], v[116:119], 0
	s_waitcnt vmcnt(2) lgkmcnt(0)
	v_mfma_f32_32x32x16_bf16 v[0:15], v[36:39], v[120:123], v[0:15]
	ds_read_b128 v[36:39], v175 offset:36864
	v_mfma_f32_32x32x16_bf16 v[16:31], v[16:19], v[116:119], 0
	s_waitcnt lgkmcnt(0)
	v_mfma_f32_32x32x16_bf16 v[16:31], v[36:39], v[120:123], v[16:31]
	ds_read_b128 v[36:39], v176 offset:32768
	s_waitcnt vmcnt(1) lgkmcnt(0)
	v_mfma_f32_32x32x16_bf16 v[0:15], v[36:39], v[124:127], v[0:15]
	ds_read_b128 v[36:39], v176 offset:36864
	s_waitcnt lgkmcnt(0)
	v_mfma_f32_32x32x16_bf16 v[16:31], v[36:39], v[124:127], v[16:31]
	ds_read_b128 v[36:39], v177 offset:32768
	s_waitcnt vmcnt(0) lgkmcnt(0)
	v_mfma_f32_32x32x16_bf16 v[0:15], v[36:39], v[112:115], v[0:15]
	ds_read_b128 v[36:39], v177 offset:36864
	s_waitcnt lgkmcnt(0)
	v_mfma_f32_32x32x16_bf16 v[16:31], v[36:39], v[112:115], v[16:31]
	s_nop 8
	v_max_f32_e32 v33, v1, v1
	v_max_f32_e32 v36, v0, v0
	v_max_f32_e32 v33, v36, v33
	v_max3_f32 v33, v33, v2, v3
	v_max3_f32 v33, v33, v4, v5
	v_max3_f32 v33, v33, v6, v7
	v_max3_f32 v33, v33, v8, v9
	v_max3_f32 v33, v33, v10, v11
	v_max3_f32 v33, v33, v12, v13
	v_max3_f32 v33, v33, v14, v15
	v_max3_f32 v33, v33, v16, v17
	v_max3_f32 v33, v33, v18, v19
	v_max3_f32 v33, v33, v20, v21
	v_max3_f32 v33, v33, v22, v23
	v_max3_f32 v33, v33, v24, v25
	v_max3_f32 v33, v33, v26, v27
	v_max3_f32 v33, v33, v28, v29
	v_max3_f32 v33, v33, v30, v31
	v_mov_b32_e32 v36, v33
	s_nop 1
	v_permlane32_swap_b32_e32 v33, v36
	v_max_f32_e32 v36, v36, v36
	v_max_f32_e32 v33, v33, v33
	v_max_f32_e32 v33, v33, v36
	v_add_f32_e32 v36, 0x7149f2ca, v33
	v_cmp_ge_f32_e32 vcc, s66, v36
	s_cmp_eq_u64 vcc, exec
	s_cbranch_scc0 .LBB0_865
	v_mov_b32_e32 v144, 0xf149f2ca
	v_mov_b32_e32 v178, 1.0

.LBB0_834:
	ds_read_b128 v[214:217], v249 offset:45056
	ds_read_b128 v[112:115], v249 offset:40960
	v_exp_f32_e32 v152, v80
	v_exp_f32_e32 v193, v81
	v_exp_f32_e32 v195, v82
	v_exp_f32_e32 v197, v83
	s_waitcnt lgkmcnt(0)
	v_mfma_f32_32x32x16_bf16 v[96:111], v[112:115], v[140:143], v[64:79]
	v_exp_f32_e32 v199, v84
	v_add_f32_e32 v80, v209, v152
	v_add_f32_e32 v80, 0, v80
	v_add_f32_e32 v81, v194, v193
	v_add_f32_e32 v80, v81, v80
	v_add_f32_e32 v81, v211, v195
	v_add_f32_e32 v80, v81, v80
	v_mfma_f32_32x32x16_bf16 v[112:127], v[214:217], v[140:143], v[64:79]
	ds_read_b128 v[214:217], v250 offset:45056
	ds_read_b128 v[218:221], v250 offset:40960
	v_add_f32_e32 v81, v192, v197
	v_exp_f32_e32 v154, v88
	v_exp_f32_e32 v155, v89
	v_add_f32_e32 v80, v81, v80
	v_add_f32_e32 v81, v212, v199
	v_add_f32_e32 v80, v81, v80
	s_waitcnt lgkmcnt(1)
	v_mfma_f32_32x32x16_bf16 v[112:127], v[214:217], v[136:139], v[112:127]
	v_exp_f32_e32 v156, v90
	v_exp_f32_e32 v157, v91
	v_exp_f32_e32 v158, v92
	v_exp_f32_e32 v159, v93
	v_exp_f32_e32 v160, v94
	v_exp_f32_e32 v161, v95
	s_waitcnt lgkmcnt(0)
	v_mfma_f32_32x32x16_bf16 v[96:111], v[218:221], v[136:139], v[96:111]
	ds_read_b128 v[214:217], v233 offset:45056
	ds_read_b128 v[218:221], v233 offset:40960
	s_waitcnt lgkmcnt(1)
	v_mfma_f32_32x32x16_bf16 v[112:127], v[214:217], v[132:135], v[112:127]
	s_waitcnt lgkmcnt(0)
	v_mfma_f32_32x32x16_bf16 v[96:111], v[218:221], v[132:135], v[96:111]
	ds_read_b128 v[214:217], v232 offset:45056
	ds_read_b128 v[218:221], v232 offset:40960
	s_waitcnt lgkmcnt(1)
	v_mfma_f32_32x32x16_bf16 v[112:127], v[214:217], v[128:131], v[112:127]
	v_exp_f32_e32 v214, v85
	v_exp_f32_e32 v215, v86
	v_exp_f32_e32 v216, v87
	v_add_f32_e32 v81, v198, v214
	v_add_f32_e32 v80, v81, v80
	v_add_f32_e32 v81, v213, v215
	v_add_f32_e32 v80, v81, v80
	v_add_f32_e32 v81, v196, v216
	v_add_f32_e32 v82, v81, v80
	v_add_f32_e32 v81, v203, v155
	v_add_f32_e32 v80, v202, v154
	s_waitcnt lgkmcnt(0)
	v_mfma_f32_32x32x16_bf16 v[96:111], v[218:221], v[128:131], v[96:111]
	v_add_f32_e32 v80, v80, v82
	v_add_f32_e32 v82, v81, v80
	v_add_f32_e64 v80, v200, v156
	v_add_f32_e64 v81, v201, v157
	v_add_f32_e32 v80, v80, v82
	v_add_f32_e32 v82, v81, v80
	v_add_f32_e32 v81, v207, v159
	v_add_f32_e32 v80, v206, v158
	v_add_f32_e32 v80, v80, v82
	v_add_f32_e32 v82, v81, v80
	v_add_f32_e32 v81, v205, v161
	v_add_f32_e32 v80, v204, v160
	v_add_f32_e32 v80, v80, v82
	v_add_f32_e32 v208, v81, v80
	v_cvt_pk_bf16_f32 v80, v209, v194
	v_cvt_pk_bf16_f32 v81, v211, v192
	v_cvt_pk_bf16_f32 v82, v212, v198
	v_cvt_pk_bf16_f32 v83, v213, v196
	v_cvt_pk_bf16_f32 v84, v202, v203
	v_cvt_pk_bf16_f32 v85, v200, v201
	v_cvt_pk_bf16_f32 v86, v206, v207
	v_cvt_pk_bf16_f32 v87, v204, v205
	v_cvt_pk_bf16_f32 v88, v152, v193
	v_cvt_pk_bf16_f32 v89, v195, v197
	v_cvt_pk_bf16_f32 v90, v199, v214
	v_cvt_pk_bf16_f32 v91, v215, v216
	v_cvt_pk_bf16_f32 v92, v154, v155
	v_cvt_pk_bf16_f32 v93, v156, v157
	v_cvt_pk_bf16_f32 v94, v158, v159
	v_cvt_pk_bf16_f32 v95, v160, v161
	v_mov_b32_e32 v210, v208
	v_permlane32_swap_b32_e32 v80, v82
	v_permlane32_swap_b32_e32 v81, v83
	v_permlane32_swap_b32_e32 v84, v86
	v_permlane32_swap_b32_e32 v85, v87
	v_permlane32_swap_b32_e32 v88, v90
	v_permlane32_swap_b32_e32 v89, v91
	v_permlane32_swap_b32_e32 v92, v94
	v_permlane32_swap_b32_e32 v93, v95
	v_permlane32_swap_b32_e32 v208, v210
	s_add_i32 s2, s19, 64
	s_and_b32 s2, s2, 0x7c0
	s_cmp_lt_u32 s21, 31
	s_cselect_b32 s3, s10, s18
	s_add_i32 s48, s3, s2
	v_lshl_add_u64 v[154:155], s[48:49], 0, v[184:185]
	v_mad_u64_u32 v[156:157], s[2:3], v154, s60, v[190:191]
	v_mad_i32_i24 v157, v155, s60, v157
	v_lshl_add_u64 v[154:155], s[48:49], 0, v[186:187]
	v_mov_b64_e32 v[192:193], s[70:71]
	global_load_dwordx4 v[178:181], v[156:157], off offset:3200
	v_mad_u64_u32 v[156:157], s[2:3], v154, s60, v[192:193]
	v_mad_i32_i24 v157, v155, s60, v157
	s_mov_b32 s91, s49
	v_lshl_add_u64 v[154:155], v[156:157], 0, s[90:91]
	v_lshl_add_u64 v[154:155], v[154:155], 0, v[188:189]
	v_add_co_u32_e32 v156, vcc, s58, v154
	s_nop 1
	v_addc_co_u32_e32 v157, vcc, 0, v155, vcc
	global_load_dwordx4 v[148:151], v[154:155], off
	s_nop 0
	global_load_dwordx2 v[146:147], v[156:157], off
	global_load_dwordx2 v[182:183], v[156:157], off offset:8
	ds_read_b64_tr_b16 v[194:195], v248 offset:0
	ds_read_b64_tr_b16 v[196:197], v248 offset:0x800
	ds_read_b64_tr_b16 v[198:199], v248 offset:0x1000
	ds_read_b64_tr_b16 v[200:201], v248 offset:0x1800
	ds_read_b64_tr_b16 v[202:203], v248 offset:0x2000
	ds_read_b64_tr_b16 v[204:205], v248 offset:0x2800
	ds_read_b64_tr_b16 v[216:217], v248 offset:0x3000
	ds_read_b64_tr_b16 v[218:219], v248 offset:0x3800
	s_waitcnt lgkmcnt(0)
	s_nop 0
	v_mfma_f32_32x32x16_bf16 v[48:63], v[80:83], v[194:197], v[48:63]
	v_exp_f32_e32 v238, v96
	v_exp_f32_e32 v194, v97
	ds_read_b64_tr_b16 v[96:97], v248 offset:0x200
	v_exp_f32_e32 v236, v98
	v_exp_f32_e32 v196, v99
	ds_read_b64_tr_b16 v[98:99], v248 offset:0xa00
	v_mfma_f32_32x32x16_bf16 v[48:63], v[84:87], v[198:201], v[48:63]
	ds_read_b64_tr_b16 v[198:199], v248 offset:0x1200
	ds_read_b64_tr_b16 v[200:201], v248 offset:0x1a00
	v_mfma_f32_32x32x16_bf16 v[48:63], v[88:91], v[202:205], v[48:63]
	ds_read_b64_tr_b16 v[202:203], v248 offset:0x2200
	ds_read_b64_tr_b16 v[204:205], v248 offset:0x2a00
	v_mfma_f32_32x32x16_bf16 v[48:63], v[92:95], v[216:219], v[48:63]
	ds_read_b64_tr_b16 v[216:217], v248 offset:0x3200
	ds_read_b64_tr_b16 v[218:219], v248 offset:0x3a00
	s_waitcnt lgkmcnt(0)
	v_mfma_f32_32x32x16_bf16 v[32:47], v[80:83], v[96:99], v[32:47]
	s_waitcnt vmcnt(4)
	ds_write_b128 v251, v[166:169] offset:32768
	ds_write_b128 v252, v[170:173]
	ds_write_b128 v231, v[174:177]
	ds_read_b64_tr_b16 v[96:97], v248 offset:0x400
	ds_read_b64_tr_b16 v[98:99], v248 offset:0xc00
	v_exp_f32_e32 v237, v100
	v_exp_f32_e32 v162, v102
	v_mfma_f32_32x32x16_bf16 v[32:47], v[84:87], v[198:201], v[32:47]
	v_exp_f32_e32 v198, v101
	ds_read_b64_tr_b16 v[100:101], v248 offset:0x1400
	v_exp_f32_e32 v200, v103
	ds_read_b64_tr_b16 v[102:103], v248 offset:0x1c00
	v_mfma_f32_32x32x16_bf16 v[32:47], v[88:91], v[202:205], v[32:47]
	ds_read_b64_tr_b16 v[202:203], v248 offset:0x2400
	ds_read_b64_tr_b16 v[204:205], v248 offset:0x2c00
	v_mfma_f32_32x32x16_bf16 v[32:47], v[92:95], v[216:219], v[32:47]
	ds_read_b64_tr_b16 v[216:217], v248 offset:0x3400
	ds_read_b64_tr_b16 v[218:219], v248 offset:0x3c00
	v_xor_b32_e32 v249, 0x10000, v249
	v_xor_b32_e32 v250, 0x10000, v250
	v_xor_b32_e32 v233, 0x10000, v233
	v_xor_b32_e32 v232, 0x10000, v232
	s_waitcnt lgkmcnt(0)
	v_mfma_f32_32x32x16_bf16 v[16:31], v[80:83], v[96:99], v[16:31]
	ds_read_b64_tr_b16 v[96:97], v248 offset:0x600
	ds_read_b64_tr_b16 v[98:99], v248 offset:0xe00
	v_exp_f32_e32 v163, v104
	v_exp_f32_e32 v164, v106
	v_mfma_f32_32x32x16_bf16 v[16:31], v[84:87], v[100:103], v[16:31]
	ds_read_b64_tr_b16 v[100:101], v248 offset:0x1600
	ds_read_b64_tr_b16 v[102:103], v248 offset:0x1e00
	v_mfma_f32_32x32x16_bf16 v[16:31], v[88:91], v[202:205], v[16:31]
	v_exp_f32_e32 v202, v105
	ds_read_b64_tr_b16 v[104:105], v248 offset:0x2600
	v_exp_f32_e32 v204, v107
	ds_read_b64_tr_b16 v[106:107], v248 offset:0x2e00
	ds_read_b64_tr_b16 v[158:159], v248 offset:0x3600
	ds_read_b64_tr_b16 v[160:161], v248 offset:0x3e00
	s_waitcnt lgkmcnt(0)
	v_mfma_f32_32x32x16_bf16 v[16:31], v[92:95], v[216:219], v[16:31]
	v_mfma_f32_32x32x16_bf16 v[0:15], v[80:83], v[96:99], v[0:15]
	v_exp_f32_e32 v165, v108
	v_exp_f32_e32 v218, v109
	v_exp_f32_e32 v235, v110
	v_exp_f32_e32 v220, v111
	v_mfma_f32_32x32x16_bf16 v[0:15], v[84:87], v[100:103], v[0:15]
	s_waitcnt lgkmcnt(0)
	s_barrier
	v_mfma_f32_32x32x16_bf16 v[0:15], v[88:91], v[104:107], v[0:15]
	v_mfma_f32_32x32x16_bf16 v[0:15], v[92:95], v[158:161], v[0:15]
	ds_read_b128 v[154:157], v249 offset:36864
	ds_read_b128 v[80:83], v249 offset:32768
	v_exp_f32_e32 v152, v113
	v_exp_f32_e32 v222, v115
	v_exp_f32_e32 v224, v117
	v_exp_f32_e32 v226, v119
	s_waitcnt lgkmcnt(0)
	v_mfma_f32_32x32x16_bf16 v[96:111], v[80:83], v[140:143], v[64:79]
	v_exp_f32_e32 v206, v121
	v_exp_f32_e32 v212, v123
	v_exp_f32_e32 v214, v125
	v_exp_f32_e32 v216, v127
	v_mfma_f32_32x32x16_bf16 v[80:95], v[154:157], v[140:143], v[64:79]
	ds_read_b128 v[154:157], v250 offset:36864
	ds_read_b128 v[158:161], v250 offset:32768
	s_waitcnt lgkmcnt(1)
	v_mfma_f32_32x32x16_bf16 v[80:95], v[154:157], v[136:139], v[80:95]
	s_waitcnt lgkmcnt(0)
	v_mfma_f32_32x32x16_bf16 v[96:111], v[158:161], v[136:139], v[96:111]
	ds_read_b128 v[154:157], v233 offset:36864
	ds_read_b128 v[158:161], v233 offset:32768
	s_waitcnt lgkmcnt(1)
	v_mfma_f32_32x32x16_bf16 v[80:95], v[154:157], v[132:135], v[80:95]
	s_waitcnt lgkmcnt(0)
	v_mfma_f32_32x32x16_bf16 v[96:111], v[158:161], v[132:135], v[96:111]
	ds_read_b128 v[154:157], v232 offset:36864
	ds_read_b128 v[158:161], v232 offset:32768
	s_waitcnt lgkmcnt(1)
	v_mfma_f32_32x32x16_bf16 v[80:95], v[154:157], v[128:131], v[80:95]
	v_exp_f32_e32 v154, v112
	v_exp_f32_e32 v155, v114
	v_exp_f32_e32 v156, v116
	v_exp_f32_e32 v157, v118
	v_add_f32_e32 v195, v238, v154
	v_add_f32_e32 v113, v195, v153
	v_add_f32_e32 v112, v194, v152
	v_add_f32_e32 v197, v236, v155
	v_add_f32_e32 v113, v112, v113
	v_add_f32_e32 v113, v197, v113
	v_add_f32_e32 v112, v196, v222
	v_add_f32_e32 v199, v237, v156
	v_add_f32_e32 v113, v112, v113
	v_add_f32_e32 v113, v199, v113
	v_add_f32_e32 v112, v198, v224
	s_waitcnt lgkmcnt(0)
	v_mfma_f32_32x32x16_bf16 v[96:111], v[158:161], v[128:131], v[96:111]
	v_exp_f32_e32 v158, v120
	v_add_f32_e32 v113, v112, v113
	v_add_f32_e32 v201, v162, v157
	v_add_f32_e32 v113, v201, v113
	v_add_f32_e32 v112, v200, v226
	v_exp_f32_e32 v159, v122
	v_add_f32_e32 v113, v112, v113
	v_add_f32_e32 v203, v163, v158
	v_add_f32_e32 v113, v203, v113
	v_add_f32_e32 v112, v202, v206
	v_exp_f32_e32 v160, v124
	v_add_f32_e32 v113, v112, v113
	v_add_f32_e32 v205, v164, v159
	v_add_f32_e32 v113, v205, v113
	v_add_f32_e32 v112, v204, v212
	v_exp_f32_e32 v161, v126
	v_add_f32_e32 v113, v112, v113
	v_add_f32_e32 v219, v165, v160
	v_add_f32_e32 v113, v219, v113
	v_add_f32_e32 v112, v218, v214
	v_add_f32_e32 v221, v235, v161
	v_add_f32_e32 v113, v112, v113
	v_add_f32_e32 v113, v221, v113
	v_add_f32_e32 v112, v220, v216
	v_add_f32_e32 v112, v112, v113
	v_mov_b32_e32 v113, v112
	v_mov_b32_e32 v211, v112
	s_nop 1
	v_permlane32_swap_b32_e32 v112, v211
	v_mov_b32_e32 v209, v112
	v_add_f32_e32 v113, v209, v211
	v_add_f32_e32 v112, v208, v210
	v_cmp_ngt_f32_e32 vcc, s59, v113
	v_cmp_ngt_f32_e64 s[2:3], s59, v112
	v_fma_f32 v114, v246, v234, v112
	s_or_b64 s[2:3], s[2:3], vcc
	v_add_f32_e32 v246, v114, v113
	s_or_b64 s[16:17], s[16:17], s[2:3]
	v_cvt_pk_bf16_f32 v112, v238, v194
	v_cvt_pk_bf16_f32 v113, v236, v196
	v_cvt_pk_bf16_f32 v114, v237, v198
	v_cvt_pk_bf16_f32 v115, v162, v200
	v_cvt_pk_bf16_f32 v116, v163, v202
	v_cvt_pk_bf16_f32 v117, v164, v204
	v_cvt_pk_bf16_f32 v118, v165, v218
	v_cvt_pk_bf16_f32 v119, v235, v220
	v_cvt_pk_bf16_f32 v120, v154, v152
	v_cvt_pk_bf16_f32 v121, v155, v222
	v_cvt_pk_bf16_f32 v122, v156, v224
	v_cvt_pk_bf16_f32 v123, v157, v226
	v_cvt_pk_bf16_f32 v124, v158, v206
	v_cvt_pk_bf16_f32 v125, v159, v212
	v_cvt_pk_bf16_f32 v126, v160, v214
	v_cvt_pk_bf16_f32 v127, v161, v216
	s_nop 0
	v_permlane32_swap_b32_e32 v112, v114
	v_permlane32_swap_b32_e32 v113, v115
	v_permlane32_swap_b32_e32 v116, v118
	v_permlane32_swap_b32_e32 v117, v119
	v_permlane32_swap_b32_e32 v120, v122
	v_permlane32_swap_b32_e32 v121, v123
	v_permlane32_swap_b32_e32 v124, v126
	v_permlane32_swap_b32_e32 v125, v127
	s_add_i32 s2, s21, -1
	s_cmp_lt_u32 s21, 30
	s_cselect_b32 s3, 0, 0xffffffe0
	s_cselect_b32 s22, s10, s18
	s_add_i32 s3, s3, s21
	s_lshl_b32 s3, s3, 6
	s_add_i32 s3, s3, s22
	s_add_i32 s48, s3, 0x80
	v_lshl_add_u64 v[158:159], s[48:49], 0, v[186:187]
	v_mad_u64_u32 v[160:161], s[22:23], v158, s60, v[192:193]
	v_mad_i32_i24 v161, v159, s60, v161
	v_lshl_add_u64 v[154:155], s[48:49], 0, v[184:185]
	v_lshl_add_u64 v[158:159], v[160:161], 0, s[90:91]
	v_mad_u64_u32 v[156:157], s[22:23], v154, s60, v[190:191]
	v_lshl_add_u64 v[158:159], v[158:159], 0, v[188:189]
	v_mad_i32_i24 v157, v155, s60, v157
	v_add_co_u32_e32 v192, vcc, s58, v158
	global_load_dwordx4 v[166:169], v[156:157], off offset:3200
	s_nop 0
	v_addc_co_u32_e32 v193, vcc, 0, v159, vcc
	global_load_dwordx4 v[170:173], v[158:159], off
	s_nop 0
	global_load_dwordx4 v[174:177], v[192:193], off
	ds_read_b64_tr_b16 v[192:193], v247 offset:0
	ds_read_b64_tr_b16 v[194:195], v247 offset:0x800
	ds_read_b64_tr_b16 v[196:197], v247 offset:0x1000
	ds_read_b64_tr_b16 v[198:199], v247 offset:0x1800
	ds_read_b64_tr_b16 v[200:201], v247 offset:0x2000
	ds_read_b64_tr_b16 v[202:203], v247 offset:0x2800
	ds_read_b64_tr_b16 v[204:205], v247 offset:0x3000
	ds_read_b64_tr_b16 v[206:207], v247 offset:0x3800
	s_waitcnt lgkmcnt(0)
	s_nop 0
	v_mfma_f32_32x32x16_bf16 v[48:63], v[112:115], v[192:195], v[48:63]
	v_exp_f32_e32 v209, v96
	v_exp_f32_e32 v194, v97
	ds_read_b64_tr_b16 v[96:97], v247 offset:0x200
	v_exp_f32_e32 v211, v98
	v_exp_f32_e32 v192, v99
	ds_read_b64_tr_b16 v[98:99], v247 offset:0xa00
	v_mfma_f32_32x32x16_bf16 v[48:63], v[116:119], v[196:199], v[48:63]
	ds_read_b64_tr_b16 v[196:197], v247 offset:0x1200
	ds_read_b64_tr_b16 v[198:199], v247 offset:0x1a00
	v_mfma_f32_32x32x16_bf16 v[48:63], v[120:123], v[200:203], v[48:63]
	ds_read_b64_tr_b16 v[200:201], v247 offset:0x2200
	ds_read_b64_tr_b16 v[202:203], v247 offset:0x2a00
	v_mfma_f32_32x32x16_bf16 v[48:63], v[124:127], v[204:207], v[48:63]
	ds_read_b64_tr_b16 v[204:205], v247 offset:0x3200
	ds_read_b64_tr_b16 v[206:207], v247 offset:0x3a00
	s_waitcnt lgkmcnt(0)
	v_mfma_f32_32x32x16_bf16 v[32:47], v[112:115], v[96:99], v[32:47]
	s_waitcnt vmcnt(3)
	ds_write_b128 v251, v[178:181] offset:40960
	ds_write_b128 v252, v[148:151] offset:16384
	ds_write_b64 v231, v[146:147] offset:16384
	ds_write_b64 v231, v[182:183] offset:16392
	ds_read_b64_tr_b16 v[96:97], v247 offset:0x400
	ds_read_b64_tr_b16 v[98:99], v247 offset:0xc00
	v_exp_f32_e32 v212, v100
	v_exp_f32_e32 v213, v102
	v_mfma_f32_32x32x16_bf16 v[32:47], v[116:119], v[196:199], v[32:47]
	v_exp_f32_e32 v198, v101
	ds_read_b64_tr_b16 v[100:101], v247 offset:0x1400
	v_exp_f32_e32 v196, v103
	ds_read_b64_tr_b16 v[102:103], v247 offset:0x1c00
	v_mfma_f32_32x32x16_bf16 v[32:47], v[120:123], v[200:203], v[32:47]
	ds_read_b64_tr_b16 v[200:201], v247 offset:0x2400
	ds_read_b64_tr_b16 v[202:203], v247 offset:0x2c00
	v_mfma_f32_32x32x16_bf16 v[32:47], v[124:127], v[204:207], v[32:47]
	ds_read_b64_tr_b16 v[204:205], v247 offset:0x3400
	ds_read_b64_tr_b16 v[206:207], v247 offset:0x3c00
	v_xor_b32_e32 v248, 0x10000, v248
	s_waitcnt lgkmcnt(0)
	v_mfma_f32_32x32x16_bf16 v[16:31], v[112:115], v[96:99], v[16:31]
	ds_read_b64_tr_b16 v[96:97], v247 offset:0x600
	ds_read_b64_tr_b16 v[98:99], v247 offset:0xe00
	v_mfma_f32_32x32x16_bf16 v[16:31], v[116:119], v[100:103], v[16:31]
	ds_read_b64_tr_b16 v[100:101], v247 offset:0x1600
	ds_read_b64_tr_b16 v[102:103], v247 offset:0x1e00
	v_mfma_f32_32x32x16_bf16 v[16:31], v[120:123], v[200:203], v[16:31]
	v_exp_f32_e32 v202, v104
	v_exp_f32_e32 v203, v105
	ds_read_b64_tr_b16 v[104:105], v247 offset:0x2600
	v_exp_f32_e32 v200, v106
	v_exp_f32_e32 v201, v107
	ds_read_b64_tr_b16 v[106:107], v247 offset:0x2e00
	ds_read_b64_tr_b16 v[218:219], v247 offset:0x3600
	v_mfma_f32_32x32x16_bf16 v[16:31], v[124:127], v[204:207], v[16:31]
	ds_read_b64_tr_b16 v[220:221], v247 offset:0x3e00
	s_waitcnt lgkmcnt(0)
	v_mfma_f32_32x32x16_bf16 v[0:15], v[112:115], v[96:99], v[0:15]
	v_exp_f32_e32 v206, v108
	v_exp_f32_e32 v207, v109
	v_exp_f32_e32 v204, v110
	v_exp_f32_e32 v205, v111
	s_andn2_b64 s[14:15], s[14:15], exec
	s_and_b64 s[22:23], s[16:17], exec
	s_addk_i32 s19, 0x80
	v_mfma_f32_32x32x16_bf16 v[0:15], v[116:119], v[100:103], v[0:15]
	s_add_i32 s21, s21, 2
	s_or_b64 s[14:15], s[14:15], s[22:23]
	s_cmp_gt_u32 s2, 32
	v_mov_b32_e32 v234, 1.0
	v_mfma_f32_32x32x16_bf16 v[0:15], v[120:123], v[104:107], v[0:15]
	v_xor_b32_e32 v247, 0x10000, v247
	v_xor_b32_e32 v251, 0x10000, v251
	v_xor_b32_e32 v252, 0x10000, v252
	v_xor_b32_e32 v231, 0x10000, v231
	s_waitcnt lgkmcnt(0)
	s_barrier
	v_mfma_f32_32x32x16_bf16 v[0:15], v[124:127], v[218:221], v[0:15]
	s_cbranch_scc0 .LBB0_834
	ds_read_b128 v[112:115], v249 offset:45056
	ds_read_b128 v[116:119], v249 offset:40960
	v_exp_f32_e32 v152, v81
	v_exp_f32_e32 v124, v84
	v_exp_f32_e32 v84, v85
	v_exp_f32_e32 v125, v86
	s_waitcnt lgkmcnt(0)
	v_mfma_f32_32x32x16_bf16 v[96:111], v[116:119], v[140:143], v[64:79]
	v_exp_f32_e32 v86, v87
	v_add_f32_e32 v199, v212, v124
	v_exp_f32_e32 v126, v88
	v_add_f32_e32 v197, v213, v125
	v_exp_f32_e32 v127, v90
	v_exp_f32_e32 v120, v93
	v_exp_f32_e32 v122, v95
	v_mfma_f32_32x32x16_bf16 v[64:79], v[112:115], v[140:143], v[64:79]
	ds_read_b128 v[112:115], v250 offset:45056
	ds_read_b128 v[116:119], v250 offset:40960
	s_waitcnt lgkmcnt(1)
	v_mfma_f32_32x32x16_bf16 v[64:79], v[112:115], v[136:139], v[64:79]
	s_waitcnt lgkmcnt(0)
	v_mfma_f32_32x32x16_bf16 v[96:111], v[116:119], v[136:139], v[96:111]
	ds_read_b128 v[112:115], v233 offset:45056
	ds_read_b128 v[116:119], v233 offset:40960
	s_waitcnt lgkmcnt(1)
	v_mfma_f32_32x32x16_bf16 v[64:79], v[112:115], v[132:135], v[64:79]
	s_waitcnt lgkmcnt(0)
	v_mfma_f32_32x32x16_bf16 v[96:111], v[116:119], v[132:135], v[96:111]
	ds_read_b128 v[112:115], v232 offset:45056
	ds_read_b128 v[116:119], v232 offset:40960
	v_cvt_pk_bf16_f32 v88, v209, v194
	s_waitcnt lgkmcnt(1)
	v_mfma_f32_32x32x16_bf16 v[64:79], v[112:115], v[128:131], v[64:79]
	v_exp_f32_e32 v112, v80
	v_exp_f32_e32 v113, v82
	v_exp_f32_e32 v114, v83
	v_add_f32_e32 v83, v202, v126
	v_add_f32_e32 v195, v209, v112
	v_pk_add_f32 v[80:81], v[194:195], v[152:153]
	v_add_f32_e32 v193, v211, v113
	v_pk_add_f32 v[80:81], v[80:81], v[80:81] op_sel_hi:[0,1]
	v_mov_b32_e32 v115, v81
	v_pk_add_f32 v[80:81], v[192:193], v[114:115]
	s_waitcnt lgkmcnt(0)
	v_mfma_f32_32x32x16_bf16 v[96:111], v[116:119], v[128:131], v[96:111]
	v_pk_add_f32 v[80:81], v[80:81], v[80:81] op_sel_hi:[0,1]
	v_mov_b32_e32 v85, v81
	v_pk_add_f32 v[80:81], v[198:199], v[84:85]
	v_exp_f32_e32 v116, v89
	v_pk_add_f32 v[80:81], v[80:81], v[80:81] op_sel_hi:[0,1]
	v_mov_b32_e32 v87, v81
	v_pk_add_f32 v[80:81], v[196:197], v[86:87]
	v_exp_f32_e32 v118, v91
	v_pk_add_f32 v[80:81], v[80:81], v[80:81] op_sel_hi:[0,1]
	v_mov_b32_e32 v82, v203
	v_mov_b32_e32 v117, v81
	v_pk_add_f32 v[80:81], v[82:83], v[116:117]
	v_exp_f32_e32 v128, v92
	v_pk_add_f32 v[80:81], v[80:81], v[80:81] op_sel_hi:[0,1]
	v_add_f32_e32 v83, v200, v127
	v_mov_b32_e32 v82, v201
	v_mov_b32_e32 v119, v81
	v_pk_add_f32 v[80:81], v[82:83], v[118:119]
	v_exp_f32_e32 v129, v94
	v_pk_add_f32 v[80:81], v[80:81], v[80:81] op_sel_hi:[0,1]
	v_add_f32_e32 v83, v206, v128
	v_mov_b32_e32 v82, v207
	v_mov_b32_e32 v121, v81
	v_pk_add_f32 v[80:81], v[82:83], v[120:121]
	v_add_f32_e32 v83, v204, v129
	v_pk_add_f32 v[80:81], v[80:81], v[80:81] op_sel_hi:[0,1]
	v_mov_b32_e32 v82, v205
	v_mov_b32_e32 v123, v81
	v_pk_add_f32 v[80:81], v[82:83], v[122:123]
	v_cvt_pk_bf16_f32 v89, v211, v192
	v_cvt_pk_bf16_f32 v90, v212, v198
	v_cvt_pk_bf16_f32 v91, v213, v196
	v_cvt_pk_bf16_f32 v92, v202, v203
	v_cvt_pk_bf16_f32 v93, v200, v201
	s_nop 0
	v_pk_add_f32 v[80:81], v[80:81], v[80:81] op_sel:[0,1] op_sel_hi:[1,0]
	v_cvt_pk_bf16_f32 v94, v206, v207
	v_cvt_pk_bf16_f32 v95, v204, v205
	v_cvt_pk_bf16_f32 v112, v112, v152
	v_cvt_pk_bf16_f32 v113, v113, v114
	v_cvt_pk_bf16_f32 v114, v124, v84
	s_nop 0
	v_mov_b32_e32 v82, v80
	v_cvt_pk_bf16_f32 v115, v125, v86
	v_cvt_pk_bf16_f32 v116, v126, v116
	v_cvt_pk_bf16_f32 v117, v127, v118
	v_cvt_pk_bf16_f32 v118, v128, v120
	v_cvt_pk_bf16_f32 v119, v129, v122
	s_nop 1
	v_permlane32_swap_b32_e32 v80, v82
	v_permlane32_swap_b32_e32 v88, v90
	v_permlane32_swap_b32_e32 v89, v91
	v_permlane32_swap_b32_e32 v92, v94
	v_permlane32_swap_b32_e32 v93, v95
	v_permlane32_swap_b32_e32 v112, v114
	v_permlane32_swap_b32_e32 v113, v115
	v_permlane32_swap_b32_e32 v116, v118
	v_permlane32_swap_b32_e32 v117, v119
	ds_read_b64_tr_b16 v[84:85], v248 offset:0
	ds_read_b64_tr_b16 v[86:87], v248 offset:0x800
	ds_read_b64_tr_b16 v[120:121], v248 offset:0x1000
	ds_read_b64_tr_b16 v[122:123], v248 offset:0x1800
	ds_read_b64_tr_b16 v[124:125], v248 offset:0x2000
	ds_read_b64_tr_b16 v[126:127], v248 offset:0x2800
	ds_read_b64_tr_b16 v[128:129], v248 offset:0x3000
	ds_read_b64_tr_b16 v[130:131], v248 offset:0x3800
	s_waitcnt lgkmcnt(0)
	s_nop 0
	v_mfma_f32_32x32x16_bf16 v[48:63], v[88:91], v[84:87], v[48:63]
	v_exp_f32_e32 v132, v96
	v_exp_f32_e32 v84, v97
	ds_read_b64_tr_b16 v[96:97], v248 offset:0x200
	v_exp_f32_e32 v133, v98
	v_exp_f32_e32 v86, v99
	ds_read_b64_tr_b16 v[98:99], v248 offset:0xa00
	v_mfma_f32_32x32x16_bf16 v[48:63], v[92:95], v[120:123], v[48:63]
	ds_read_b64_tr_b16 v[120:121], v248 offset:0x1200
	ds_read_b64_tr_b16 v[122:123], v248 offset:0x1a00
	v_mfma_f32_32x32x16_bf16 v[48:63], v[112:115], v[124:127], v[48:63]
	ds_read_b64_tr_b16 v[124:125], v248 offset:0x2200
	ds_read_b64_tr_b16 v[126:127], v248 offset:0x2a00
	v_mfma_f32_32x32x16_bf16 v[48:63], v[116:119], v[128:131], v[48:63]
	ds_read_b64_tr_b16 v[128:129], v248 offset:0x3200
	ds_read_b64_tr_b16 v[130:131], v248 offset:0x3a00
	s_waitcnt lgkmcnt(0)
	v_mfma_f32_32x32x16_bf16 v[32:47], v[88:91], v[96:99], v[32:47]
	ds_read_b64_tr_b16 v[96:97], v248 offset:0x400
	ds_read_b64_tr_b16 v[98:99], v248 offset:0xc00
	v_exp_f32_e32 v134, v100
	v_exp_f32_e32 v135, v102
	v_mfma_f32_32x32x16_bf16 v[32:47], v[92:95], v[120:123], v[32:47]
	v_mfma_f32_32x32x16_bf16 v[32:47], v[112:115], v[124:127], v[32:47]
	v_mfma_f32_32x32x16_bf16 v[32:47], v[116:119], v[128:131], v[32:47]
	v_exp_f32_e32 v128, v101
	ds_read_b64_tr_b16 v[100:101], v248 offset:0x1400
	v_exp_f32_e32 v130, v103
	ds_read_b64_tr_b16 v[102:103], v248 offset:0x1c00
	ds_read_b64_tr_b16 v[120:121], v248 offset:0x2400
	ds_read_b64_tr_b16 v[122:123], v248 offset:0x2c00
	ds_read_b64_tr_b16 v[124:125], v248 offset:0x3400
	ds_read_b64_tr_b16 v[126:127], v248 offset:0x3c00
	s_waitcnt lgkmcnt(0)
	v_mfma_f32_32x32x16_bf16 v[16:31], v[88:91], v[96:99], v[16:31]
	ds_read_b64_tr_b16 v[96:97], v248 offset:0x600
	ds_read_b64_tr_b16 v[98:99], v248 offset:0xe00
	v_exp_f32_e32 v136, v104
	v_exp_f32_e32 v137, v106
	v_mfma_f32_32x32x16_bf16 v[16:31], v[92:95], v[100:103], v[16:31]
	ds_read_b64_tr_b16 v[100:101], v248 offset:0x1600
	ds_read_b64_tr_b16 v[102:103], v248 offset:0x1e00
	v_mfma_f32_32x32x16_bf16 v[16:31], v[112:115], v[120:123], v[16:31]
	v_mfma_f32_32x32x16_bf16 v[16:31], v[116:119], v[124:127], v[16:31]
	v_exp_f32_e32 v124, v105
	ds_read_b64_tr_b16 v[104:105], v248 offset:0x2600
	v_exp_f32_e32 v126, v107
	ds_read_b64_tr_b16 v[106:107], v248 offset:0x2e00
	ds_read_b64_tr_b16 v[120:121], v248 offset:0x3600
	ds_read_b64_tr_b16 v[122:123], v248 offset:0x3e00
	s_waitcnt lgkmcnt(0)
	v_mfma_f32_32x32x16_bf16 v[0:15], v[88:91], v[96:99], v[0:15]
	v_exp_f32_e32 v152, v65
	v_exp_f32_e32 v88, v109
	v_exp_f32_e32 v109, v66
	v_exp_f32_e32 v90, v111
	v_exp_f32_e32 v111, v70
	v_exp_f32_e32 v96, v71
	v_add_f32_e32 v87, v133, v109
	v_mfma_f32_32x32x16_bf16 v[0:15], v[92:95], v[100:103], v[0:15]
	v_exp_f32_e32 v92, v67
	v_exp_f32_e32 v94, v69
	v_exp_f32_e32 v98, v73
	v_add_f32_e32 v131, v135, v111
	v_exp_f32_e32 v100, v75
	v_exp_f32_e32 v102, v77
	v_cvt_pk_bf16_f32 v66, v132, v84
	v_mfma_f32_32x32x16_bf16 v[0:15], v[112:115], v[104:107], v[0:15]
	v_exp_f32_e32 v106, v108
	v_exp_f32_e32 v108, v64
	v_exp_f32_e32 v107, v110
	v_exp_f32_e32 v110, v68
	v_exp_f32_e32 v112, v72
	v_add_f32_e32 v85, v132, v108
	v_pk_add_f32 v[64:65], v[84:85], v[152:153]
	v_add_f32_e32 v129, v134, v110
	v_pk_add_f32 v[64:65], v[64:65], v[64:65] op_sel_hi:[0,1]
	v_mov_b32_e32 v93, v65
	v_pk_add_f32 v[64:65], v[86:87], v[92:93]
	v_exp_f32_e32 v113, v74
	v_pk_add_f32 v[64:65], v[64:65], v[64:65] op_sel_hi:[0,1]
	v_mov_b32_e32 v95, v65
	v_pk_add_f32 v[64:65], v[128:129], v[94:95]
	v_add_f32_e32 v125, v136, v112
	v_pk_add_f32 v[64:65], v[64:65], v[64:65] op_sel_hi:[0,1]
	v_mov_b32_e32 v97, v65
	v_pk_add_f32 v[64:65], v[130:131], v[96:97]
	v_exp_f32_e32 v114, v76
	v_pk_add_f32 v[64:65], v[64:65], v[64:65] op_sel_hi:[0,1]
	v_mov_b32_e32 v99, v65
	v_pk_add_f32 v[64:65], v[124:125], v[98:99]
	v_add_f32_e32 v127, v137, v113
	v_pk_add_f32 v[64:65], v[64:65], v[64:65] op_sel_hi:[0,1]
	v_mov_b32_e32 v101, v65
	v_pk_add_f32 v[64:65], v[126:127], v[100:101]
	v_exp_f32_e32 v115, v78
	v_pk_add_f32 v[64:65], v[64:65], v[64:65] op_sel_hi:[0,1]
	v_exp_f32_e32 v104, v79
	v_add_f32_e32 v89, v106, v114
	v_mov_b32_e32 v103, v65
	v_pk_add_f32 v[64:65], v[88:89], v[102:103]
	v_add_f32_e32 v91, v107, v115
	v_pk_add_f32 v[64:65], v[64:65], v[64:65] op_sel_hi:[0,1]
	v_mov_b32_e32 v105, v65
	v_pk_add_f32 v[64:65], v[90:91], v[104:105]
	v_mfma_f32_32x32x16_bf16 v[0:15], v[116:119], v[120:123], v[0:15]
	v_pk_add_f32 v[64:65], v[64:65], v[64:65] op_sel:[0,1] op_sel_hi:[1,0]
	v_cvt_pk_bf16_f32 v67, v133, v86
	v_cvt_pk_bf16_f32 v68, v134, v128
	v_cvt_pk_bf16_f32 v69, v135, v130
	v_cvt_pk_bf16_f32 v70, v136, v124
	v_cvt_pk_bf16_f32 v71, v137, v126
	s_nop 0
	v_mov_b32_e32 v83, v64
	s_nop 1
	v_permlane32_swap_b32_e32 v64, v83
	v_mov_b32_e32 v81, v64
	v_pk_add_f32 v[64:65], v[80:81], v[82:83]
	v_cvt_pk_bf16_f32 v72, v106, v88
	v_cvt_pk_bf16_f32 v73, v107, v90
	v_cvt_pk_bf16_f32 v74, v108, v152
	v_cvt_pk_bf16_f32 v75, v109, v92
	v_cvt_pk_bf16_f32 v76, v110, v94
	s_nop 0
	v_cmp_ngt_f32_e32 vcc, s59, v65
	v_cmp_ngt_f32_e64 s[2:3], s59, v64
	s_or_b64 s[2:3], s[2:3], vcc
	s_or_b64 s[2:3], s[14:15], s[2:3]
	v_cvt_pk_bf16_f32 v77, v111, v96
	v_cvt_pk_bf16_f32 v78, v112, v98
	v_cvt_pk_bf16_f32 v79, v113, v100
	v_cvt_pk_bf16_f32 v80, v114, v102
	v_cvt_pk_bf16_f32 v81, v115, v104
	v_permlane32_swap_b32_e32 v66, v68
	v_permlane32_swap_b32_e32 v67, v69
	v_permlane32_swap_b32_e32 v70, v72
	v_permlane32_swap_b32_e32 v71, v73
	v_permlane32_swap_b32_e32 v74, v76
	v_permlane32_swap_b32_e32 v75, v77
	v_permlane32_swap_b32_e32 v78, v80
	v_permlane32_swap_b32_e32 v79, v81
	ds_read_b64_tr_b16 v[82:83], v247 offset:0
	ds_read_b64_tr_b16 v[84:85], v247 offset:0x800
	ds_read_b64_tr_b16 v[86:87], v247 offset:0x1000
	ds_read_b64_tr_b16 v[88:89], v247 offset:0x1800
	ds_read_b64_tr_b16 v[90:91], v247 offset:0x2000
	ds_read_b64_tr_b16 v[92:93], v247 offset:0x2800
	ds_read_b64_tr_b16 v[94:95], v247 offset:0x3000
	ds_read_b64_tr_b16 v[96:97], v247 offset:0x3800
	s_waitcnt lgkmcnt(0)
	s_nop 0
	v_mfma_f32_32x32x16_bf16 v[48:63], v[66:69], v[82:85], v[48:63]
	ds_read_b64_tr_b16 v[82:83], v247 offset:0x200
	ds_read_b64_tr_b16 v[84:85], v247 offset:0xa00
	v_mfma_f32_32x32x16_bf16 v[48:63], v[70:73], v[86:89], v[48:63]
	ds_read_b64_tr_b16 v[86:87], v247 offset:0x1200
	ds_read_b64_tr_b16 v[88:89], v247 offset:0x1a00
	v_mfma_f32_32x32x16_bf16 v[48:63], v[74:77], v[90:93], v[48:63]
	ds_read_b64_tr_b16 v[90:91], v247 offset:0x2200
	ds_read_b64_tr_b16 v[92:93], v247 offset:0x2a00
	v_mfma_f32_32x32x16_bf16 v[48:63], v[78:81], v[94:97], v[48:63]
	ds_read_b64_tr_b16 v[94:95], v247 offset:0x3200
	ds_read_b64_tr_b16 v[96:97], v247 offset:0x3a00
	s_waitcnt lgkmcnt(0)
	v_mfma_f32_32x32x16_bf16 v[32:47], v[66:69], v[82:85], v[32:47]
	ds_read_b64_tr_b16 v[82:83], v247 offset:0x400
	ds_read_b64_tr_b16 v[84:85], v247 offset:0xc00
	v_mfma_f32_32x32x16_bf16 v[32:47], v[70:73], v[86:89], v[32:47]
	ds_read_b64_tr_b16 v[86:87], v247 offset:0x1400
	ds_read_b64_tr_b16 v[88:89], v247 offset:0x1c00
	v_mfma_f32_32x32x16_bf16 v[32:47], v[74:77], v[90:93], v[32:47]
	ds_read_b64_tr_b16 v[90:91], v247 offset:0x2400
	ds_read_b64_tr_b16 v[92:93], v247 offset:0x2c00
	v_mfma_f32_32x32x16_bf16 v[32:47], v[78:81], v[94:97], v[32:47]
	ds_read_b64_tr_b16 v[94:95], v247 offset:0x3400
	ds_read_b64_tr_b16 v[96:97], v247 offset:0x3c00
	s_waitcnt lgkmcnt(0)
	v_mfma_f32_32x32x16_bf16 v[16:31], v[66:69], v[82:85], v[16:31]
	ds_read_b64_tr_b16 v[82:83], v247 offset:0x600
	ds_read_b64_tr_b16 v[84:85], v247 offset:0xe00
	v_mfma_f32_32x32x16_bf16 v[16:31], v[70:73], v[86:89], v[16:31]
	ds_read_b64_tr_b16 v[86:87], v247 offset:0x1600
	ds_read_b64_tr_b16 v[88:89], v247 offset:0x1e00
	v_mfma_f32_32x32x16_bf16 v[16:31], v[74:77], v[90:93], v[16:31]
	ds_read_b64_tr_b16 v[90:91], v247 offset:0x2600
	ds_read_b64_tr_b16 v[92:93], v247 offset:0x2e00
	v_mfma_f32_32x32x16_bf16 v[16:31], v[78:81], v[94:97], v[16:31]
	ds_read_b64_tr_b16 v[94:95], v247 offset:0x3600
	ds_read_b64_tr_b16 v[96:97], v247 offset:0x3e00
	s_waitcnt lgkmcnt(0)
	v_mfma_f32_32x32x16_bf16 v[0:15], v[66:69], v[82:85], v[0:15]
	v_mfma_f32_32x32x16_bf16 v[0:15], v[70:73], v[86:89], v[0:15]
	v_mfma_f32_32x32x16_bf16 v[0:15], v[74:77], v[90:93], v[0:15]
	v_mfma_f32_32x32x16_bf16 v[0:15], v[78:81], v[94:97], v[0:15]
	s_setprio 0
	v_and_b32_e32 v247, 0xfffeffff, v247
	v_and_b32_e32 v248, 0xfffeffff, v248
	v_and_b32_e32 v249, 0xfffeffff, v249
	v_and_b32_e32 v250, 0xfffeffff, v250
	v_and_b32_e32 v251, 0xfffeffff, v251
	v_and_b32_e32 v252, 0xfffeffff, v252
	v_and_b32_e32 v231, 0xfffeffff, v231
	v_and_b32_e32 v232, 0xfffeffff, v232
	v_and_b32_e32 v233, 0xfffeffff, v233
	v_cndmask_b32_e64 v66, 0, 1, s[2:3]
	v_cmp_ne_u32_e32 vcc, 0, v66
	s_cmp_lg_u64 vcc, 0
	s_cselect_b64 s[2:3], -1, 0
	v_cmp_eq_u32_e32 vcc, 0, v245
	s_and_b64 s[14:15], vcc, s[2:3]
	s_and_saveexec_b64 s[2:3], s[14:15]
	ds_write_b32 v153, v229 offset:51200
	s_or_b64 exec, exec, s[2:3]
	s_waitcnt vmcnt(0) lgkmcnt(0)
	s_barrier
	ds_read_b32 v66, v153 offset:51200
	s_waitcnt lgkmcnt(0)
	s_barrier
	v_cmp_eq_u32_e32 vcc, 0, v66
	s_cbranch_vccnz .LBB0_861
	v_mbcnt_lo_u32_b32 v0, -1, 0
	v_mbcnt_hi_u32_b32 v0, -1, v0
	v_mov_b64_e32 v[14:15], s[94:95]
	v_add_u32_e32 v35, s33, v0
	v_mov_b32_e32 v33, v153
	v_ashrrev_i32_e32 v0, 1, v35
	v_and_b32_e32 v34, 31, v35
	v_and_b32_e32 v0, 0xffffffe0, v0
	v_ashrrev_i32_e32 v1, 31, v0
	v_or_b32_e32 v152, s8, v34
	v_ashrrev_i32_e32 v188, 3, v35
	v_lshlrev_b32_e32 v16, 3, v35
	v_lshl_add_u64 v[12:13], v[152:153], 0, v[0:1]
	v_and_b32_e32 v0, 56, v16
	v_ashrrev_i32_e32 v189, 31, v188
	v_lshlrev_b32_e32 v32, 1, v0
	v_lshl_add_u64 v[0:1], v[188:189], 0, s[10:11]
	v_ashrrev_i32_e32 v190, 4, v35
	v_mad_u64_u32 v[2:3], s[2:3], v0, s60, v[14:15]
	v_mad_i32_i24 v3, v1, s60, v3
	v_ashrrev_i32_e32 v191, 31, v190
	v_lshl_add_u64 v[0:1], v[2:3], 0, v[32:33]
	v_lshl_add_u64 v[2:3], v[190:191], 0, s[10:11]
	v_mov_b64_e32 v[4:5], s[70:71]
	v_mad_u64_u32 v[4:5], s[2:3], v2, s60, v[4:5]
	v_and_b32_e32 v6, 0x78, v16
	v_mad_i32_i24 v5, v3, s60, v5
	s_mov_b32 s91, s49
	v_lshl_add_u64 v[2:3], v[4:5], 0, s[90:91]
	v_lshlrev_b32_e32 v152, 1, v6
	v_lshl_add_u64 v[8:9], v[2:3], 0, v[152:153]
	global_load_dwordx4 v[0:3], v[0:1], off offset:3200
	s_nop 0
	global_load_dwordx4 v[4:7], v[8:9], off
	v_add_co_u32_e32 v8, vcc, s58, v8
	v_mad_u64_u32 v[14:15], s[2:3], v12, s60, v[14:15]
	s_nop 0
	v_addc_co_u32_e32 v9, vcc, 0, v9, vcc
	global_load_dwordx4 v[8:11], v[8:9], off
	v_lshrrev_b32_e32 v17, 1, v35
	v_mad_i32_i24 v15, v13, s60, v15
	v_and_b32_e32 v186, 16, v17
	v_mov_b32_e32 v187, v153
	v_lshl_add_u64 v[12:13], v[14:15], 0, v[186:187]
	global_load_dwordx4 v[116:119], v[12:13], off offset:2176
	global_load_dwordx4 v[120:123], v[12:13], off offset:2208
	global_load_dwordx4 v[124:127], v[12:13], off offset:2240
	global_load_dwordx4 v[112:115], v[12:13], off offset:2272
	v_and_b32_e32 v19, 0xfffff0, v190
	v_lshlrev_b32_e32 v20, 1, v190
	v_lshrrev_b32_e32 v21, 1, v190
	v_and_b32_e32 v23, 3, v190
	v_add_u32_e32 v24, 32, v190
	v_and_b32_e32 v14, 0x70, v35
	v_lshlrev_b32_e32 v18, 7, v188
	v_bfe_u32 v22, v16, 5, 2
	v_and_b32_e32 v33, 0x70, v16
	v_and_or_b32 v16, v20, 8, v19
	v_and_or_b32 v19, v21, 4, v23
	v_and_b32_e32 v20, 0xfffff0, v24
	v_lshlrev_b32_e32 v21, 1, v24
	v_lshl_add_u32 v40, v34, 7, 0
	v_bitop3_b32 v17, v17, v33, 16 bitop3:0x6c
	v_bitop3_b32 v14, v32, v18, v14 bitop3:0xde
	v_lshrrev_b32_e32 v16, 1, v16
	v_lshlrev_b32_e32 v18, 6, v19
	v_and_or_b32 v19, v21, 8, v20
	v_add_u32_e32 v197, v40, v17
	v_or_b32_e32 v16, v16, v22
	v_lshrrev_b32_e32 v17, 1, v19
	v_lshlrev_b32_e32 v15, 4, v35
	v_add_u32_e32 v198, 0, v14
	v_lshlrev_b32_e32 v14, 9, v16
	v_or_b32_e32 v16, v17, v22
	v_and_b32_e32 v15, 48, v15
	v_lshlrev_b32_e32 v12, 9, v16
	v_or3_b32 v14, v14, v18, v15
	v_or3_b32 v12, v12, v18, v15
	v_add_u32_e32 v199, 0, v14
	v_add_u32_e32 v200, 0, v12
	v_bitop3_b32 v20, v186, v33, 32 bitop3:0x36
	v_add_u32_e32 v201, v40, v20
	v_bitop3_b32 v41, v186, v33, 64 bitop3:0x36
	v_add_u32_e32 v202, v40, v41
	v_bitop3_b32 v33, v186, v33, s88 bitop3:0x36
	v_add_u32_e32 v203, v40, v33
	s_waitcnt vmcnt(6)
	ds_write_b128 v198, v[0:3] offset:32768
	s_waitcnt vmcnt(5)
	ds_write_b128 v199, v[4:7]
	s_waitcnt vmcnt(4)
	ds_write_b128 v200, v[8:11]
	s_waitcnt lgkmcnt(0)
	s_barrier
	ds_read_b128 v[0:3], v197 offset:32768
	ds_read_b128 v[16:19], v197 offset:36864
	ds_read_b128 v[36:39], v201 offset:32768
	s_waitcnt vmcnt(3) lgkmcnt(2)
	v_mfma_f32_32x32x16_bf16 v[0:15], v[0:3], v[116:119], 0
	s_waitcnt vmcnt(2) lgkmcnt(0)
	v_mfma_f32_32x32x16_bf16 v[0:15], v[36:39], v[120:123], v[0:15]
	ds_read_b128 v[36:39], v201 offset:36864
	v_mfma_f32_32x32x16_bf16 v[16:31], v[16:19], v[116:119], 0
	s_waitcnt lgkmcnt(0)
	v_mfma_f32_32x32x16_bf16 v[16:31], v[36:39], v[120:123], v[16:31]
	ds_read_b128 v[36:39], v202 offset:32768
	s_waitcnt vmcnt(1) lgkmcnt(0)
	v_mfma_f32_32x32x16_bf16 v[0:15], v[36:39], v[124:127], v[0:15]
	ds_read_b128 v[36:39], v202 offset:36864
	s_waitcnt lgkmcnt(0)
	v_mfma_f32_32x32x16_bf16 v[16:31], v[36:39], v[124:127], v[16:31]
	ds_read_b128 v[36:39], v203 offset:32768
	s_waitcnt vmcnt(0) lgkmcnt(0)
	v_mfma_f32_32x32x16_bf16 v[0:15], v[36:39], v[112:115], v[0:15]
	ds_read_b128 v[36:39], v203 offset:36864
	s_waitcnt lgkmcnt(0)
	v_mfma_f32_32x32x16_bf16 v[16:31], v[36:39], v[112:115], v[16:31]
	s_nop 8
	v_max_f32_e32 v33, v1, v1
	v_max_f32_e32 v36, v0, v0
	v_max_f32_e32 v33, v36, v33
	v_max3_f32 v33, v33, v2, v3
	v_max3_f32 v33, v33, v4, v5
	v_max3_f32 v33, v33, v6, v7
	v_max3_f32 v33, v33, v8, v9
	v_max3_f32 v33, v33, v10, v11
	v_max3_f32 v33, v33, v12, v13
	v_max3_f32 v33, v33, v14, v15
	v_max3_f32 v33, v33, v16, v17
	v_max3_f32 v33, v33, v18, v19
	v_max3_f32 v33, v33, v20, v21
	v_max3_f32 v33, v33, v22, v23
	v_max3_f32 v33, v33, v24, v25
	v_max3_f32 v33, v33, v26, v27
	v_max3_f32 v33, v33, v28, v29
	v_max3_f32 v33, v33, v30, v31
	v_mov_b32_e32 v36, v33
	s_nop 1
	v_permlane32_swap_b32_e32 v33, v36
	v_max_f32_e32 v36, v36, v36
	v_max_f32_e32 v33, v33, v33
	v_max_f32_e32 v33, v33, v36
	v_add_f32_e32 v36, 0x7149f2ca, v33
	v_cmp_ge_f32_e32 vcc, s66, v36
	s_cmp_eq_u64 vcc, exec
	s_cbranch_scc0 .LBB0_867
	v_mov_b32_e32 v184, 0xf149f2ca
	v_mov_b32_e32 v204, 1.0
